# GEMM K-loops: one static s_setprio 1 for the trailing wave half per unit instead of per-MFMA-block toggling
# speedup vs baseline: 1.0072x; 1.0028x over previous
; #define PG8_STAGE(bufoff, gbase, voff) do { _Pragma("unroll") for (int _i = 0; _i < 2; ++_i) \
;         __builtin_amdgcn_global_load_lds((const unsigned*)((const char*)(gbase) + (voff)[_i]), (PG8_LAS unsigned*)(lds + (bufoff) + ldsw + _i * 8192), 16, 0, 0); } while (0)
; #define PG8_LDA(dst, b, h) do { _Pragma("unroll") for (int m = 0; m < 4; ++m) _Pragma("unroll") for (int k = 0; k < 2; ++k) dst[m][k] = *(const PG8_LAS bf16x8*)(lds + PG8_SA(b, h) + aoff + m * 2048 + k * 1024); } while (0)
; #define PG8_LDB(dst, b, h) do { _Pragma("unroll") for (int n = 0; n < 2; ++n) _Pragma("unroll") for (int k = 0; k < 2; ++k) dst[n][k] = *(const PG8_LAS bf16x8*)(lds + PG8_SB(b, h) + boff + n * 2048 + k * 1024); } while (0)
; #define PG8_MMA(ai, bj, At, Bt) do { __builtin_amdgcn_s_setprio(1); _Pragma("unroll") for (int m = 0; m < 4; ++m) _Pragma("unroll") for (int n = 0; n < 2; ++n) _Pragma("unroll") for (int k = 0; k < 2; ++k) \
;         acc[ai][bj][m][n] = __builtin_amdgcn_mfma_f32_16x16x32_bf16(Bt[n][k], At[m][k], acc[ai][bj][m][n], 0, 0, 0); __builtin_amdgcn_s_setprio(0); } while (0)
; #define PG8_WAIT_V(n) asm volatile("s_waitcnt vmcnt(" #n ")" ::: "memory")
; #define PG8_WAIT_L(n) asm volatile("s_waitcnt lgkmcnt(" #n ")" ::: "memory")
; #define PG8_BAR __builtin_amdgcn_s_barrier()
; #define PG8_SCHED __builtin_amdgcn_sched_barrier(0)
; template <class Epi, class Sched, bool ALIGN_EPI = false, bool SP2 = false>
; __device__ __forceinline__ void gemm_phase(PG8_LAS unsigned char* lds, const Gemm g, const Sched& S, const Epi& E) {
;     ...
;             PG8_LDB(B0, 0, 0); PG8_LDB(B1, 0, 1); PG8_SCHED; PG8_LDA(At, 0, 0); PG8_STAGE(PG8_SA(1, 1), a1 + hstep, voffA);
;             PG8_WAIT_V(8); PG8_WAIT_L(0); PG8_BAR; PG8_MMA(0, 0, At, B0); PG8_MMA(0, 1, At, B1); PG8_BAR; PG8_SCHED;
;     ...
; #pragma unroll
;         for (int a = 0; a < 2; ++a)
; #pragma unroll
;             for (int b = 0; b < 2; ++b)
; #pragma unroll
;                 for (int m = 0; m < 4; ++m)
; #pragma unroll
;                     for (int n = 0; n < 2; ++n) acc[a][b][m][n] = (f32x4){0.f, 0.f, 0.f, 0.f};
.LBB0_388:
	s_add_i32 s28, s50, -2
	s_add_u32 s18, s18, 0x80
	s_addc_u32 s19, s19, 0
	s_add_u32 s29, s12, 0x100
	v_mov_b32_e32 v2, 0
	s_addc_u32 s43, s13, 0
	s_mov_b32 s12, 0
	v_mov_b32_e32 v3, v2
	v_mov_b32_e32 v4, v2
	v_mov_b32_e32 v5, v2
	v_mov_b32_e32 v6, v2
	v_mov_b32_e32 v7, v2
	v_mov_b32_e32 v8, v2
	v_mov_b32_e32 v9, v2
	v_mov_b32_e32 v18, v2
	v_mov_b32_e32 v19, v2
	v_mov_b32_e32 v20, v2
	v_mov_b32_e32 v21, v2
	v_mov_b32_e32 v22, v2
	v_mov_b32_e32 v23, v2
	v_mov_b32_e32 v24, v2
	v_mov_b32_e32 v25, v2
	v_mov_b32_e32 v34, v2
	v_mov_b32_e32 v35, v2
	v_mov_b32_e32 v36, v2
	v_mov_b32_e32 v37, v2
	v_mov_b32_e32 v38, v2
	v_mov_b32_e32 v39, v2
	v_mov_b32_e32 v40, v2
	v_mov_b32_e32 v41, v2
	v_mov_b32_e32 v50, v2
	v_mov_b32_e32 v51, v2
	v_mov_b32_e32 v52, v2
	v_mov_b32_e32 v53, v2
	v_mov_b32_e32 v54, v2
	v_mov_b32_e32 v55, v2
	v_mov_b32_e32 v56, v2
	v_mov_b32_e32 v57, v2
	v_mov_b32_e32 v10, v2
	v_mov_b32_e32 v11, v2
	v_mov_b32_e32 v12, v2
	v_mov_b32_e32 v13, v2
	v_mov_b32_e32 v14, v2
	v_mov_b32_e32 v15, v2
	v_mov_b32_e32 v16, v2
	v_mov_b32_e32 v17, v2
	v_mov_b32_e32 v26, v2
	v_mov_b32_e32 v27, v2
	v_mov_b32_e32 v28, v2
	v_mov_b32_e32 v29, v2
	v_mov_b32_e32 v30, v2
	v_mov_b32_e32 v31, v2
	v_mov_b32_e32 v32, v2
	v_mov_b32_e32 v33, v2
	v_mov_b32_e32 v42, v2
	v_mov_b32_e32 v43, v2
	v_mov_b32_e32 v44, v2
	v_mov_b32_e32 v45, v2
	v_mov_b32_e32 v46, v2
	v_mov_b32_e32 v47, v2
	v_mov_b32_e32 v48, v2
	v_mov_b32_e32 v49, v2
	v_mov_b32_e32 v58, v2
	v_mov_b32_e32 v59, v2
	v_mov_b32_e32 v60, v2
	v_mov_b32_e32 v61, v2
	v_mov_b32_e32 v62, v2
	v_mov_b32_e32 v63, v2
	v_mov_b32_e32 v64, v2
	v_mov_b32_e32 v65, v2
	v_mov_b32_e32 v66, v2
	v_mov_b32_e32 v67, v2
	v_mov_b32_e32 v68, v2
	v_mov_b32_e32 v69, v2
	v_mov_b32_e32 v70, v2
	v_mov_b32_e32 v71, v2
	v_mov_b32_e32 v72, v2
	v_mov_b32_e32 v73, v2
	v_mov_b32_e32 v82, v2
	v_mov_b32_e32 v83, v2
	v_mov_b32_e32 v84, v2
	v_mov_b32_e32 v85, v2
	v_mov_b32_e32 v86, v2
	v_mov_b32_e32 v87, v2
	v_mov_b32_e32 v88, v2
	v_mov_b32_e32 v89, v2
	v_mov_b32_e32 v98, v2
	v_mov_b32_e32 v99, v2
	v_mov_b32_e32 v100, v2
	v_mov_b32_e32 v101, v2
	v_mov_b32_e32 v102, v2
	v_mov_b32_e32 v103, v2
	v_mov_b32_e32 v104, v2
	v_mov_b32_e32 v105, v2
	v_mov_b32_e32 v114, v2
	v_mov_b32_e32 v115, v2
	v_mov_b32_e32 v116, v2
	v_mov_b32_e32 v117, v2
	v_mov_b32_e32 v118, v2
	v_mov_b32_e32 v119, v2
	v_mov_b32_e32 v120, v2
	v_mov_b32_e32 v121, v2
	v_mov_b32_e32 v74, v2
	v_mov_b32_e32 v75, v2
	v_mov_b32_e32 v76, v2
	v_mov_b32_e32 v77, v2
	v_mov_b32_e32 v78, v2
	v_mov_b32_e32 v79, v2
	v_mov_b32_e32 v80, v2
	v_mov_b32_e32 v81, v2
	v_mov_b32_e32 v90, v2
	v_mov_b32_e32 v91, v2
	v_mov_b32_e32 v92, v2
	v_mov_b32_e32 v93, v2
	v_mov_b32_e32 v94, v2
	v_mov_b32_e32 v95, v2
	v_mov_b32_e32 v96, v2
	v_mov_b32_e32 v97, v2
	v_mov_b32_e32 v106, v2
	v_mov_b32_e32 v107, v2
	v_mov_b32_e32 v108, v2
	v_mov_b32_e32 v109, v2
	v_mov_b32_e32 v110, v2
	v_mov_b32_e32 v111, v2
	v_mov_b32_e32 v112, v2
	v_mov_b32_e32 v113, v2
	v_mov_b32_e32 v122, v2
	v_mov_b32_e32 v123, v2
	v_mov_b32_e32 v124, v2
	v_mov_b32_e32 v125, v2
	v_mov_b32_e32 v126, v2
	v_mov_b32_e32 v127, v2
	v_mov_b32_e32 v128, v2
	v_mov_b32_e32 v129, v2
	s_and_b64 vcc, exec, s[40:41]
	s_cbranch_vccnz .Lprio_skip_0
	s_setprio 1
.Lprio_skip_0:
.LBB0_389:
	v_or_b32_e32 v140, 0x10000, v148
	v_add_u32_e32 v144, 0x10400, v148
	ds_read_b128 v[140:143], v140
	ds_read_b128 v[160:163], v144
	v_add_u32_e32 v144, 0x10800, v148
	v_add_u32_e32 v145, 0x10c00, v148
	ds_read_b128 v[164:167], v144
	ds_read_b128 v[168:171], v145
	v_or_b32_e32 v144, 0x14000, v148
	v_add_u32_e32 v145, 0x14400, v148
	ds_read_b128 v[172:175], v144
	ds_read_b128 v[176:179], v145
	v_add_u32_e32 v144, 0x14800, v148
	s_add_i32 s51, s12, 2
	v_add_u32_e32 v145, 0x14c00, v148
	ds_read_b128 v[180:183], v144
	ds_read_b128 v[206:209], v145
	s_add_u32 s59, s18, 0x80
	s_addc_u32 s13, s19, 0
	s_cmp_eq_u32 s28, s12
	s_cselect_b32 s12, s44, s59
	s_cselect_b32 s13, s45, s13
	s_cselect_b32 s69, s47, s43
	s_cselect_b32 s68, s46, s29
	v_lshl_add_u64 v[144:145], s[18:19], 0, v[136:137]
	s_add_i32 m0, s48, 0xc000
	ds_read_b128 v[210:213], v147
	ds_read_b128 v[214:217], v147 offset:1024
	ds_read_b128 v[218:221], v147 offset:2048
	ds_read_b128 v[222:225], v147 offset:3072
	ds_read_b128 v[226:229], v147 offset:4096
	ds_read_b128 v[230:233], v147 offset:5120
	ds_read_b128 v[234:237], v147 offset:6144
	ds_read_b128 v[238:241], v147 offset:7168
	global_load_lds_dwordx4 v[144:145], off
	v_lshl_add_u64 v[144:145], s[18:19], 0, v[138:139]
	s_mov_b32 m0, s15
	s_nop 0
	global_load_lds_dwordx4 v[144:145], off
	s_waitcnt vmcnt(8)
	s_waitcnt lgkmcnt(0)
	s_barrier
; #define PG8_STAGE(bufoff, gbase, voff) do { _Pragma("unroll") for (int _i = 0; _i < 2; ++_i) \
;         __builtin_amdgcn_global_load_lds((const unsigned*)((const char*)(gbase) + (voff)[_i]), (PG8_LAS unsigned*)(lds + (bufoff) + ldsw + _i * 8192), 16, 0, 0); } while (0)
; #define PG8_LDA(dst, b, h) do { _Pragma("unroll") for (int m = 0; m < 4; ++m) _Pragma("unroll") for (int k = 0; k < 2; ++k) dst[m][k] = *(const PG8_LAS bf16x8*)(lds + PG8_SA(b, h) + aoff + m * 2048 + k * 1024); } while (0)
; #define PG8_MMA(ai, bj, At, Bt) do { __builtin_amdgcn_s_setprio(1); _Pragma("unroll") for (int m = 0; m < 4; ++m) _Pragma("unroll") for (int n = 0; n < 2; ++n) _Pragma("unroll") for (int k = 0; k < 2; ++k) \
;         acc[ai][bj][m][n] = __builtin_amdgcn_mfma_f32_16x16x32_bf16(Bt[n][k], At[m][k], acc[ai][bj][m][n], 0, 0, 0); __builtin_amdgcn_s_setprio(0); } while (0)
; #define PG8_WAIT_V(n) asm volatile("s_waitcnt vmcnt(" #n ")" ::: "memory")
; #define PG8_WAIT_L(n) asm volatile("s_waitcnt lgkmcnt(" #n ")" ::: "memory")
; #define PG8_BAR __builtin_amdgcn_s_barrier()
; #define PG8_SCHED __builtin_amdgcn_sched_barrier(0)
; template <class Epi, class Sched, bool ALIGN_EPI = false, bool SP2 = false>
; __device__ __forceinline__ void gemm_phase(PG8_LAS unsigned char* lds, const Gemm g, const Sched& S, const Epi& E) {
;     ...
;             PG8_WAIT_V(8); PG8_WAIT_L(0); PG8_BAR; PG8_MMA(0, 0, At, B0); PG8_MMA(0, 1, At, B1); PG8_BAR; PG8_SCHED;
;             PG8_LDA(At, 0, 1); PG8_STAGE(PG8_SB(0, 0), b2, voffB); PG8_STAGE(PG8_SB(0, 1), b2 + hstep, voffB); PG8_STAGE(PG8_SA(0, 0), a2, voffA);
;             PG8_WAIT_V(8); PG8_WAIT_L(0); PG8_BAR; PG8_MMA(1, 0, At, B0); PG8_MMA(1, 1, At, B1); PG8_BAR; PG8_SCHED;
	s_waitcnt lgkmcnt(0)
	v_mfma_f32_16x16x32_bf16 v[126:129], v[140:143], v[210:213], v[126:129]
	v_mfma_f32_16x16x32_bf16 v[122:125], v[164:167], v[210:213], v[122:125]
	v_mfma_f32_16x16x32_bf16 v[110:113], v[140:143], v[218:221], v[110:113]
	v_mfma_f32_16x16x32_bf16 v[106:109], v[164:167], v[218:221], v[106:109]
	v_mfma_f32_16x16x32_bf16 v[94:97], v[140:143], v[226:229], v[94:97]
	v_mfma_f32_16x16x32_bf16 v[90:93], v[164:167], v[226:229], v[90:93]
	v_mfma_f32_16x16x32_bf16 v[78:81], v[140:143], v[234:237], v[78:81]
	v_mfma_f32_16x16x32_bf16 v[74:77], v[164:167], v[234:237], v[74:77]
	v_mfma_f32_16x16x32_bf16 v[126:129], v[160:163], v[214:217], v[126:129]
	v_mfma_f32_16x16x32_bf16 v[122:125], v[168:171], v[214:217], v[122:125]
	v_mfma_f32_16x16x32_bf16 v[110:113], v[160:163], v[222:225], v[110:113]
	v_mfma_f32_16x16x32_bf16 v[106:109], v[168:171], v[222:225], v[106:109]
	v_mfma_f32_16x16x32_bf16 v[94:97], v[160:163], v[230:233], v[94:97]
	v_mfma_f32_16x16x32_bf16 v[90:93], v[168:171], v[230:233], v[90:93]
	v_mfma_f32_16x16x32_bf16 v[78:81], v[160:163], v[238:241], v[78:81]
	v_mfma_f32_16x16x32_bf16 v[74:77], v[168:171], v[238:241], v[74:77]
	v_mfma_f32_16x16x32_bf16 v[118:121], v[172:175], v[210:213], v[118:121]
	v_mfma_f32_16x16x32_bf16 v[114:117], v[180:183], v[210:213], v[114:117]
	v_mfma_f32_16x16x32_bf16 v[102:105], v[172:175], v[218:221], v[102:105]
	v_mfma_f32_16x16x32_bf16 v[98:101], v[180:183], v[218:221], v[98:101]
	v_mfma_f32_16x16x32_bf16 v[86:89], v[172:175], v[226:229], v[86:89]
	v_mfma_f32_16x16x32_bf16 v[82:85], v[180:183], v[226:229], v[82:85]
	v_mfma_f32_16x16x32_bf16 v[70:73], v[172:175], v[234:237], v[70:73]
	v_mfma_f32_16x16x32_bf16 v[66:69], v[180:183], v[234:237], v[66:69]
	v_mfma_f32_16x16x32_bf16 v[118:121], v[176:179], v[214:217], v[118:121]
	v_mfma_f32_16x16x32_bf16 v[114:117], v[206:209], v[214:217], v[114:117]
	v_mfma_f32_16x16x32_bf16 v[102:105], v[176:179], v[222:225], v[102:105]
	v_mfma_f32_16x16x32_bf16 v[98:101], v[206:209], v[222:225], v[98:101]
	v_mfma_f32_16x16x32_bf16 v[86:89], v[176:179], v[230:233], v[86:89]
	v_mfma_f32_16x16x32_bf16 v[82:85], v[206:209], v[230:233], v[82:85]
	v_mfma_f32_16x16x32_bf16 v[70:73], v[176:179], v[238:241], v[70:73]
	v_mfma_f32_16x16x32_bf16 v[66:69], v[206:209], v[238:241], v[66:69]
	s_barrier
	s_mov_b32 m0, s49
	v_lshl_add_u64 v[144:145], s[68:69], 0, v[0:1]
	v_lshl_add_u64 v[156:157], s[68:69], 0, v[134:135]
	s_add_u32 s68, s68, s54
	ds_read_b128 v[210:213], v147 offset:16384
	ds_read_b128 v[214:217], v147 offset:17408
	ds_read_b128 v[218:221], v147 offset:18432
	ds_read_b128 v[222:225], v147 offset:19456
	ds_read_b128 v[226:229], v147 offset:20480
	ds_read_b128 v[230:233], v147 offset:21504
	ds_read_b128 v[234:237], v147 offset:22528
	ds_read_b128 v[238:241], v147 offset:23552
	global_load_lds_dwordx4 v[144:145], off
	s_mov_b32 m0, s53
	s_addc_u32 s69, s69, 0
	global_load_lds_dwordx4 v[156:157], off
	v_lshl_add_u64 v[192:193], s[68:69], 0, v[0:1]
	s_mov_b32 m0, s64
	v_lshl_add_u64 v[194:195], s[68:69], 0, v[134:135]
	global_load_lds_dwordx4 v[192:193], off
	s_mov_b32 m0, s65
	v_lshl_add_u64 v[242:243], s[12:13], 0, v[130:131]
	global_load_lds_dwordx4 v[194:195], off
	s_mov_b32 m0, s48
	v_lshl_add_u64 v[244:245], s[12:13], 0, v[132:133]
	global_load_lds_dwordx4 v[242:243], off
	s_mov_b32 m0, s30
	s_nop 0
	global_load_lds_dwordx4 v[244:245], off
	s_waitcnt vmcnt(8)
	s_waitcnt lgkmcnt(0)
	s_barrier
	s_waitcnt lgkmcnt(0)
	v_mfma_f32_16x16x32_bf16 v[62:65], v[140:143], v[210:213], v[62:65]
	v_mfma_f32_16x16x32_bf16 v[58:61], v[164:167], v[210:213], v[58:61]
	v_mfma_f32_16x16x32_bf16 v[46:49], v[140:143], v[218:221], v[46:49]
	v_mfma_f32_16x16x32_bf16 v[42:45], v[164:167], v[218:221], v[42:45]
	v_mfma_f32_16x16x32_bf16 v[30:33], v[140:143], v[226:229], v[30:33]
	v_mfma_f32_16x16x32_bf16 v[26:29], v[164:167], v[226:229], v[26:29]
	v_mfma_f32_16x16x32_bf16 v[14:17], v[140:143], v[234:237], v[14:17]
	v_mfma_f32_16x16x32_bf16 v[10:13], v[164:167], v[234:237], v[10:13]
	v_mfma_f32_16x16x32_bf16 v[62:65], v[160:163], v[214:217], v[62:65]
	v_mfma_f32_16x16x32_bf16 v[58:61], v[168:171], v[214:217], v[58:61]
	v_mfma_f32_16x16x32_bf16 v[46:49], v[160:163], v[222:225], v[46:49]
	v_mfma_f32_16x16x32_bf16 v[42:45], v[168:171], v[222:225], v[42:45]
	v_mfma_f32_16x16x32_bf16 v[30:33], v[160:163], v[230:233], v[30:33]
	v_mfma_f32_16x16x32_bf16 v[26:29], v[168:171], v[230:233], v[26:29]
	v_mfma_f32_16x16x32_bf16 v[14:17], v[160:163], v[238:241], v[14:17]
	v_mfma_f32_16x16x32_bf16 v[10:13], v[168:171], v[238:241], v[10:13]
	v_mfma_f32_16x16x32_bf16 v[54:57], v[172:175], v[210:213], v[54:57]
	v_mfma_f32_16x16x32_bf16 v[50:53], v[180:183], v[210:213], v[50:53]
	v_mfma_f32_16x16x32_bf16 v[38:41], v[172:175], v[218:221], v[38:41]
	v_mfma_f32_16x16x32_bf16 v[34:37], v[180:183], v[218:221], v[34:37]
	v_mfma_f32_16x16x32_bf16 v[22:25], v[172:175], v[226:229], v[22:25]
	v_mfma_f32_16x16x32_bf16 v[18:21], v[180:183], v[226:229], v[18:21]
	v_mfma_f32_16x16x32_bf16 v[6:9], v[172:175], v[234:237], v[6:9]
	v_mfma_f32_16x16x32_bf16 v[2:5], v[180:183], v[234:237], v[2:5]
	v_mfma_f32_16x16x32_bf16 v[54:57], v[176:179], v[214:217], v[54:57]
	v_mfma_f32_16x16x32_bf16 v[50:53], v[206:209], v[214:217], v[50:53]
	v_mfma_f32_16x16x32_bf16 v[38:41], v[176:179], v[222:225], v[38:41]
	v_mfma_f32_16x16x32_bf16 v[34:37], v[206:209], v[222:225], v[34:37]
	v_mfma_f32_16x16x32_bf16 v[22:25], v[176:179], v[230:233], v[22:25]
	v_mfma_f32_16x16x32_bf16 v[18:21], v[206:209], v[230:233], v[18:21]
	v_mfma_f32_16x16x32_bf16 v[6:9], v[176:179], v[238:241], v[6:9]
	v_mfma_f32_16x16x32_bf16 v[2:5], v[206:209], v[238:241], v[2:5]
	s_barrier
; #define PG8_STAGE(bufoff, gbase, voff) do { _Pragma("unroll") for (int _i = 0; _i < 2; ++_i) \
;         __builtin_amdgcn_global_load_lds((const unsigned*)((const char*)(gbase) + (voff)[_i]), (PG8_LAS unsigned*)(lds + (bufoff) + ldsw + _i * 8192), 16, 0, 0); } while (0)
; #define PG8_LDA(dst, b, h) do { _Pragma("unroll") for (int m = 0; m < 4; ++m) _Pragma("unroll") for (int k = 0; k < 2; ++k) dst[m][k] = *(const PG8_LAS bf16x8*)(lds + PG8_SA(b, h) + aoff + m * 2048 + k * 1024); } while (0)
; #define PG8_LDB(dst, b, h) do { _Pragma("unroll") for (int n = 0; n < 2; ++n) _Pragma("unroll") for (int k = 0; k < 2; ++k) dst[n][k] = *(const PG8_LAS bf16x8*)(lds + PG8_SB(b, h) + boff + n * 2048 + k * 1024); } while (0)
; #define PG8_MMA(ai, bj, At, Bt) do { __builtin_amdgcn_s_setprio(1); _Pragma("unroll") for (int m = 0; m < 4; ++m) _Pragma("unroll") for (int n = 0; n < 2; ++n) _Pragma("unroll") for (int k = 0; k < 2; ++k) \
;         acc[ai][bj][m][n] = __builtin_amdgcn_mfma_f32_16x16x32_bf16(Bt[n][k], At[m][k], acc[ai][bj][m][n], 0, 0, 0); __builtin_amdgcn_s_setprio(0); } while (0)
; #define PG8_WAIT_V(n) asm volatile("s_waitcnt vmcnt(" #n ")" ::: "memory")
; #define PG8_WAIT_L(n) asm volatile("s_waitcnt lgkmcnt(" #n ")" ::: "memory")
; #define PG8_BAR __builtin_amdgcn_s_barrier()
; #define PG8_SCHED __builtin_amdgcn_sched_barrier(0)
; template <class Epi, class Sched, bool ALIGN_EPI = false, bool SP2 = false>
; __device__ __forceinline__ void gemm_phase(PG8_LAS unsigned char* lds, const Gemm g, const Sched& S, const Epi& E) {
;     ...
;             PG8_LDB(B0, 1, 0); PG8_LDB(B1, 1, 1); PG8_SCHED; PG8_LDA(At, 1, 0); PG8_STAGE(PG8_SA(0, 1), a2 + hstep, voffA);
;             PG8_WAIT_V(8); PG8_WAIT_L(0); PG8_BAR; PG8_MMA(0, 0, At, B0); PG8_MMA(0, 1, At, B1); PG8_BAR; PG8_SCHED;
	v_or_b32_e32 v140, 0x18000, v148
	v_add_u32_e32 v158, 0x18400, v148
	ds_read_b128 v[140:143], v140
	ds_read_b128 v[160:163], v158
	v_add_u32_e32 v158, 0x18800, v148
	v_add_u32_e32 v168, 0x18c00, v148
	ds_read_b128 v[164:167], v158
	ds_read_b128 v[168:171], v168
	v_or_b32_e32 v158, 0x1c000, v148
	v_add_u32_e32 v176, 0x1c400, v148
	ds_read_b128 v[172:175], v158
	ds_read_b128 v[176:179], v176
	v_add_u32_e32 v158, 0x1c800, v148
	v_add_u32_e32 v205, 0x1cc00, v148
	ds_read_b128 v[180:183], v158
	ds_read_b128 v[206:209], v205
	s_add_u32 s12, s12, s54
	s_addc_u32 s13, s13, 0
	s_mov_b32 m0, s31
	v_lshl_add_u64 v[246:247], s[12:13], 0, v[130:131]
	ds_read_b128 v[210:213], v147 offset:32768
	ds_read_b128 v[214:217], v147 offset:33792
	ds_read_b128 v[218:221], v147 offset:34816
	ds_read_b128 v[222:225], v147 offset:35840
	ds_read_b128 v[226:229], v147 offset:36864
	ds_read_b128 v[230:233], v147 offset:37888
	ds_read_b128 v[234:237], v147 offset:38912
	ds_read_b128 v[238:241], v147 offset:39936
	global_load_lds_dwordx4 v[246:247], off
	v_lshl_add_u64 v[246:247], s[12:13], 0, v[132:133]
	s_mov_b32 m0, s52
	s_nop 0
	global_load_lds_dwordx4 v[246:247], off
	s_waitcnt vmcnt(8)
	s_waitcnt lgkmcnt(0)
	s_barrier
	s_waitcnt lgkmcnt(0)
	v_mfma_f32_16x16x32_bf16 v[126:129], v[140:143], v[210:213], v[126:129]
	v_mfma_f32_16x16x32_bf16 v[122:125], v[164:167], v[210:213], v[122:125]
	v_mfma_f32_16x16x32_bf16 v[110:113], v[140:143], v[218:221], v[110:113]
	v_mfma_f32_16x16x32_bf16 v[106:109], v[164:167], v[218:221], v[106:109]
	v_mfma_f32_16x16x32_bf16 v[94:97], v[140:143], v[226:229], v[94:97]
	v_mfma_f32_16x16x32_bf16 v[90:93], v[164:167], v[226:229], v[90:93]
	v_mfma_f32_16x16x32_bf16 v[78:81], v[140:143], v[234:237], v[78:81]
	v_mfma_f32_16x16x32_bf16 v[74:77], v[164:167], v[234:237], v[74:77]
	v_mfma_f32_16x16x32_bf16 v[126:129], v[160:163], v[214:217], v[126:129]
	v_mfma_f32_16x16x32_bf16 v[122:125], v[168:171], v[214:217], v[122:125]
	v_mfma_f32_16x16x32_bf16 v[110:113], v[160:163], v[222:225], v[110:113]
	v_mfma_f32_16x16x32_bf16 v[106:109], v[168:171], v[222:225], v[106:109]
	v_mfma_f32_16x16x32_bf16 v[94:97], v[160:163], v[230:233], v[94:97]
	v_mfma_f32_16x16x32_bf16 v[90:93], v[168:171], v[230:233], v[90:93]
	v_mfma_f32_16x16x32_bf16 v[78:81], v[160:163], v[238:241], v[78:81]
	v_mfma_f32_16x16x32_bf16 v[74:77], v[168:171], v[238:241], v[74:77]
	v_mfma_f32_16x16x32_bf16 v[118:121], v[172:175], v[210:213], v[118:121]
	v_mfma_f32_16x16x32_bf16 v[114:117], v[180:183], v[210:213], v[114:117]
	v_mfma_f32_16x16x32_bf16 v[102:105], v[172:175], v[218:221], v[102:105]
	v_mfma_f32_16x16x32_bf16 v[98:101], v[180:183], v[218:221], v[98:101]
	v_mfma_f32_16x16x32_bf16 v[86:89], v[172:175], v[226:229], v[86:89]
	v_mfma_f32_16x16x32_bf16 v[82:85], v[180:183], v[226:229], v[82:85]
	v_mfma_f32_16x16x32_bf16 v[70:73], v[172:175], v[234:237], v[70:73]
	v_mfma_f32_16x16x32_bf16 v[66:69], v[180:183], v[234:237], v[66:69]
	v_mfma_f32_16x16x32_bf16 v[118:121], v[176:179], v[214:217], v[118:121]
	v_mfma_f32_16x16x32_bf16 v[114:117], v[206:209], v[214:217], v[114:117]
	v_mfma_f32_16x16x32_bf16 v[102:105], v[176:179], v[222:225], v[102:105]
	v_mfma_f32_16x16x32_bf16 v[98:101], v[206:209], v[222:225], v[98:101]
	v_mfma_f32_16x16x32_bf16 v[86:89], v[176:179], v[230:233], v[86:89]
	v_mfma_f32_16x16x32_bf16 v[82:85], v[206:209], v[230:233], v[82:85]
	v_mfma_f32_16x16x32_bf16 v[70:73], v[176:179], v[238:241], v[70:73]
	v_mfma_f32_16x16x32_bf16 v[66:69], v[206:209], v[238:241], v[66:69]
	s_barrier
; #define PG8_STAGE(bufoff, gbase, voff) do { _Pragma("unroll") for (int _i = 0; _i < 2; ++_i) \
;         __builtin_amdgcn_global_load_lds((const unsigned*)((const char*)(gbase) + (voff)[_i]), (PG8_LAS unsigned*)(lds + (bufoff) + ldsw + _i * 8192), 16, 0, 0); } while (0)
; #define PG8_LDA(dst, b, h) do { _Pragma("unroll") for (int m = 0; m < 4; ++m) _Pragma("unroll") for (int k = 0; k < 2; ++k) dst[m][k] = *(const PG8_LAS bf16x8*)(lds + PG8_SA(b, h) + aoff + m * 2048 + k * 1024); } while (0)
; #define PG8_MMA(ai, bj, At, Bt) do { __builtin_amdgcn_s_setprio(1); _Pragma("unroll") for (int m = 0; m < 4; ++m) _Pragma("unroll") for (int n = 0; n < 2; ++n) _Pragma("unroll") for (int k = 0; k < 2; ++k) \
;         acc[ai][bj][m][n] = __builtin_amdgcn_mfma_f32_16x16x32_bf16(Bt[n][k], At[m][k], acc[ai][bj][m][n], 0, 0, 0); __builtin_amdgcn_s_setprio(0); } while (0)
; #define PG8_WAIT_V(n) asm volatile("s_waitcnt vmcnt(" #n ")" ::: "memory")
; #define PG8_WAIT_L(n) asm volatile("s_waitcnt lgkmcnt(" #n ")" ::: "memory")
; #define PG8_BAR __builtin_amdgcn_s_barrier()
; #define PG8_SCHED __builtin_amdgcn_sched_barrier(0)
; template <class Epi, class Sched, bool ALIGN_EPI = false, bool SP2 = false>
; __device__ __forceinline__ void gemm_phase(PG8_LAS unsigned char* lds, const Gemm g, const Sched& S, const Epi& E) {
;     ...
;         for (int t = 0; t < nt; t += 2) {
;     ...
;             PG8_LDA(At, 1, 1); PG8_STAGE(PG8_SB(1, 0), b3, voffB); PG8_STAGE(PG8_SB(1, 1), b3 + hstep, voffB); PG8_STAGE(PG8_SA(1, 0), a3, voffA);
;             PG8_WAIT_V(8); PG8_WAIT_L(0); PG8_BAR; PG8_MMA(1, 0, At, B0); PG8_MMA(1, 1, At, B1); PG8_BAR; PG8_SCHED;
	s_mov_b32 m0, s0
	v_lshl_add_u64 v[144:145], v[144:145], 0, s[60:61]
	ds_read_b128 v[210:213], v147 offset:49152
	ds_read_b128 v[214:217], v147 offset:50176
	ds_read_b128 v[218:221], v147 offset:51200
	ds_read_b128 v[222:225], v147 offset:52224
	ds_read_b128 v[226:229], v147 offset:53248
	ds_read_b128 v[230:233], v147 offset:54272
	ds_read_b128 v[234:237], v147 offset:55296
	ds_read_b128 v[238:241], v147 offset:56320
	global_load_lds_dwordx4 v[144:145], off
	v_lshl_add_u64 v[144:145], v[156:157], 0, s[60:61]
	s_mov_b32 m0, s1
	s_nop 0
	global_load_lds_dwordx4 v[144:145], off
	v_lshl_add_u64 v[144:145], v[192:193], 0, s[60:61]
	s_mov_b32 m0, s16
	s_nop 0
	global_load_lds_dwordx4 v[144:145], off
	v_lshl_add_u64 v[144:145], v[194:195], 0, s[60:61]
	s_mov_b32 m0, s17
	s_nop 0
	global_load_lds_dwordx4 v[144:145], off
	v_lshl_add_u64 v[144:145], v[242:243], 0, s[60:61]
	s_mov_b32 m0, s36
	s_nop 0
	global_load_lds_dwordx4 v[144:145], off
	v_lshl_add_u64 v[144:145], v[244:245], 0, s[60:61]
	s_mov_b32 m0, s37
	s_nop 0
	global_load_lds_dwordx4 v[144:145], off
	s_waitcnt vmcnt(8)
	s_waitcnt lgkmcnt(0)
	s_barrier
	s_waitcnt lgkmcnt(0)
	v_mfma_f32_16x16x32_bf16 v[62:65], v[140:143], v[210:213], v[62:65]
	v_mfma_f32_16x16x32_bf16 v[58:61], v[164:167], v[210:213], v[58:61]
	v_mfma_f32_16x16x32_bf16 v[46:49], v[140:143], v[218:221], v[46:49]
	v_mfma_f32_16x16x32_bf16 v[42:45], v[164:167], v[218:221], v[42:45]
	v_mfma_f32_16x16x32_bf16 v[30:33], v[140:143], v[226:229], v[30:33]
	v_mfma_f32_16x16x32_bf16 v[26:29], v[164:167], v[226:229], v[26:29]
	v_mfma_f32_16x16x32_bf16 v[14:17], v[140:143], v[234:237], v[14:17]
	v_mfma_f32_16x16x32_bf16 v[10:13], v[164:167], v[234:237], v[10:13]
	v_mfma_f32_16x16x32_bf16 v[62:65], v[160:163], v[214:217], v[62:65]
	v_mfma_f32_16x16x32_bf16 v[58:61], v[168:171], v[214:217], v[58:61]
	v_mfma_f32_16x16x32_bf16 v[46:49], v[160:163], v[222:225], v[46:49]
	v_mfma_f32_16x16x32_bf16 v[42:45], v[168:171], v[222:225], v[42:45]
	v_mfma_f32_16x16x32_bf16 v[30:33], v[160:163], v[230:233], v[30:33]
	v_mfma_f32_16x16x32_bf16 v[26:29], v[168:171], v[230:233], v[26:29]
	v_mfma_f32_16x16x32_bf16 v[14:17], v[160:163], v[238:241], v[14:17]
	v_mfma_f32_16x16x32_bf16 v[10:13], v[168:171], v[238:241], v[10:13]
	v_mfma_f32_16x16x32_bf16 v[54:57], v[172:175], v[210:213], v[54:57]
	v_mfma_f32_16x16x32_bf16 v[50:53], v[180:183], v[210:213], v[50:53]
	v_mfma_f32_16x16x32_bf16 v[38:41], v[172:175], v[218:221], v[38:41]
	v_mfma_f32_16x16x32_bf16 v[34:37], v[180:183], v[218:221], v[34:37]
	v_mfma_f32_16x16x32_bf16 v[22:25], v[172:175], v[226:229], v[22:25]
	v_mfma_f32_16x16x32_bf16 v[18:21], v[180:183], v[226:229], v[18:21]
	v_mfma_f32_16x16x32_bf16 v[6:9], v[172:175], v[234:237], v[6:9]
	v_mfma_f32_16x16x32_bf16 v[2:5], v[180:183], v[234:237], v[2:5]
	v_mfma_f32_16x16x32_bf16 v[54:57], v[176:179], v[214:217], v[54:57]
	v_mfma_f32_16x16x32_bf16 v[50:53], v[206:209], v[214:217], v[50:53]
	v_mfma_f32_16x16x32_bf16 v[38:41], v[176:179], v[222:225], v[38:41]
	v_mfma_f32_16x16x32_bf16 v[34:37], v[206:209], v[222:225], v[34:37]
	v_mfma_f32_16x16x32_bf16 v[22:25], v[176:179], v[230:233], v[22:25]
	v_mfma_f32_16x16x32_bf16 v[18:21], v[206:209], v[230:233], v[18:21]
	v_mfma_f32_16x16x32_bf16 v[6:9], v[176:179], v[238:241], v[6:9]
	v_mfma_f32_16x16x32_bf16 v[2:5], v[206:209], v[238:241], v[2:5]
	s_barrier
	s_add_u32 s18, s18, 0x100
	s_addc_u32 s19, s19, 0
	s_add_u32 s29, s29, 0x100
	s_addc_u32 s43, s43, 0
	s_cmp_ge_i32 s51, s50
	s_mov_b32 s12, s51
	s_cbranch_scc0 .LBB0_389
	s_setprio 0
	v_readlane_b32 s68, v253, 55
	v_readlane_b32 s69, v253, 56
	s_and_b64 vcc, exec, s[40:41]
	s_cbranch_vccz .LBB0_392

; #define PG8_STAGE(bufoff, gbase, voff) do { _Pragma("unroll") for (int _i = 0; _i < 2; ++_i) \
;         __builtin_amdgcn_global_load_lds((const unsigned*)((const char*)(gbase) + (voff)[_i]), (PG8_LAS unsigned*)(lds + (bufoff) + ldsw + _i * 8192), 16, 0, 0); } while (0)
; #define PG8_LDA(dst, b, h) do { _Pragma("unroll") for (int m = 0; m < 4; ++m) _Pragma("unroll") for (int k = 0; k < 2; ++k) dst[m][k] = *(const PG8_LAS bf16x8*)(lds + PG8_SA(b, h) + aoff + m * 2048 + k * 1024); } while (0)
; #define PG8_LDB(dst, b, h) do { _Pragma("unroll") for (int n = 0; n < 2; ++n) _Pragma("unroll") for (int k = 0; k < 2; ++k) dst[n][k] = *(const PG8_LAS bf16x8*)(lds + PG8_SB(b, h) + boff + n * 2048 + k * 1024); } while (0)
; #define PG8_MMA(ai, bj, At, Bt) do { __builtin_amdgcn_s_setprio(1); _Pragma("unroll") for (int m = 0; m < 4; ++m) _Pragma("unroll") for (int n = 0; n < 2; ++n) _Pragma("unroll") for (int k = 0; k < 2; ++k) \
;         acc[ai][bj][m][n] = __builtin_amdgcn_mfma_f32_16x16x32_bf16(Bt[n][k], At[m][k], acc[ai][bj][m][n], 0, 0, 0); __builtin_amdgcn_s_setprio(0); } while (0)
; #define PG8_WAIT_V(n) asm volatile("s_waitcnt vmcnt(" #n ")" ::: "memory")
; #define PG8_WAIT_L(n) asm volatile("s_waitcnt lgkmcnt(" #n ")" ::: "memory")
; #define PG8_BAR __builtin_amdgcn_s_barrier()
; #define PG8_SCHED __builtin_amdgcn_sched_barrier(0)
; template <class Epi, class Sched, bool ALIGN_EPI = false, bool SP2 = false>
; __device__ __forceinline__ void gemm_phase(PG8_LAS unsigned char* lds, const Gemm g, const Sched& S, const Epi& E) {
;     ...
;             PG8_LDB(B0, 0, 0); PG8_LDB(B1, 0, 1); PG8_SCHED; PG8_LDA(At, 0, 0); PG8_STAGE(PG8_SA(1, 1), a1 + hstep, voffA);
;             PG8_WAIT_V(8); PG8_WAIT_L(0); PG8_BAR; PG8_MMA(0, 0, At, B0); PG8_MMA(0, 1, At, B1); PG8_BAR; PG8_SCHED;
;     ...
; #pragma unroll
;         for (int a = 0; a < 2; ++a)
; #pragma unroll
;             for (int b = 0; b < 2; ++b)
; #pragma unroll
;                 for (int m = 0; m < 4; ++m)
; #pragma unroll
;                     for (int n = 0; n < 2; ++n) acc[a][b][m][n] = (f32x4){0.f, 0.f, 0.f, 0.f};
.LBB0_415:
	s_add_i32 s50, s63, -2
	s_add_u32 s18, s12, 0x80
	s_addc_u32 s19, s13, 0
	s_add_u32 s28, s28, 0x100
	v_mov_b32_e32 v2, 0
	s_addc_u32 s29, s29, 0
	s_mov_b32 s12, 0
	v_mov_b32_e32 v3, v2
	v_mov_b32_e32 v4, v2
	v_mov_b32_e32 v5, v2
	v_mov_b32_e32 v10, v2
	v_mov_b32_e32 v11, v2
	v_mov_b32_e32 v12, v2
	v_mov_b32_e32 v13, v2
	v_mov_b32_e32 v18, v2
	v_mov_b32_e32 v19, v2
	v_mov_b32_e32 v20, v2
	v_mov_b32_e32 v21, v2
	v_mov_b32_e32 v26, v2
	v_mov_b32_e32 v27, v2
	v_mov_b32_e32 v28, v2
	v_mov_b32_e32 v29, v2
	v_mov_b32_e32 v34, v2
	v_mov_b32_e32 v35, v2
	v_mov_b32_e32 v36, v2
	v_mov_b32_e32 v37, v2
	v_mov_b32_e32 v42, v2
	v_mov_b32_e32 v43, v2
	v_mov_b32_e32 v44, v2
	v_mov_b32_e32 v45, v2
	v_mov_b32_e32 v50, v2
	v_mov_b32_e32 v51, v2
	v_mov_b32_e32 v52, v2
	v_mov_b32_e32 v53, v2
	v_mov_b32_e32 v58, v2
	v_mov_b32_e32 v59, v2
	v_mov_b32_e32 v60, v2
	v_mov_b32_e32 v61, v2
	v_mov_b32_e32 v6, v2
	v_mov_b32_e32 v7, v2
	v_mov_b32_e32 v8, v2
	v_mov_b32_e32 v9, v2
	v_mov_b32_e32 v14, v2
	v_mov_b32_e32 v15, v2
	v_mov_b32_e32 v16, v2
	v_mov_b32_e32 v17, v2
	v_mov_b32_e32 v22, v2
	v_mov_b32_e32 v23, v2
	v_mov_b32_e32 v24, v2
	v_mov_b32_e32 v25, v2
	v_mov_b32_e32 v30, v2
	v_mov_b32_e32 v31, v2
	v_mov_b32_e32 v32, v2
	v_mov_b32_e32 v33, v2
	v_mov_b32_e32 v38, v2
	v_mov_b32_e32 v39, v2
	v_mov_b32_e32 v40, v2
	v_mov_b32_e32 v41, v2
	v_mov_b32_e32 v46, v2
	v_mov_b32_e32 v47, v2
	v_mov_b32_e32 v48, v2
	v_mov_b32_e32 v49, v2
	v_mov_b32_e32 v54, v2
	v_mov_b32_e32 v55, v2
	v_mov_b32_e32 v56, v2
	v_mov_b32_e32 v57, v2
	v_mov_b32_e32 v62, v2
	v_mov_b32_e32 v63, v2
	v_mov_b32_e32 v64, v2
	v_mov_b32_e32 v65, v2
	v_mov_b32_e32 v66, v2
	v_mov_b32_e32 v67, v2
	v_mov_b32_e32 v68, v2
	v_mov_b32_e32 v69, v2
	v_mov_b32_e32 v74, v2
	v_mov_b32_e32 v75, v2
	v_mov_b32_e32 v76, v2
	v_mov_b32_e32 v77, v2
	v_mov_b32_e32 v82, v2
	v_mov_b32_e32 v83, v2
	v_mov_b32_e32 v84, v2
	v_mov_b32_e32 v85, v2
	v_mov_b32_e32 v90, v2
	v_mov_b32_e32 v91, v2
	v_mov_b32_e32 v92, v2
	v_mov_b32_e32 v93, v2
	v_mov_b32_e32 v98, v2
	v_mov_b32_e32 v99, v2
	v_mov_b32_e32 v100, v2
	v_mov_b32_e32 v101, v2
	v_mov_b32_e32 v106, v2
	v_mov_b32_e32 v107, v2
	v_mov_b32_e32 v108, v2
	v_mov_b32_e32 v109, v2
	v_mov_b32_e32 v114, v2
	v_mov_b32_e32 v115, v2
	v_mov_b32_e32 v116, v2
	v_mov_b32_e32 v117, v2
	v_mov_b32_e32 v122, v2
	v_mov_b32_e32 v123, v2
	v_mov_b32_e32 v124, v2
	v_mov_b32_e32 v125, v2
	v_mov_b32_e32 v70, v2
	v_mov_b32_e32 v71, v2
	v_mov_b32_e32 v72, v2
	v_mov_b32_e32 v73, v2
	v_mov_b32_e32 v78, v2
	v_mov_b32_e32 v79, v2
	v_mov_b32_e32 v80, v2
	v_mov_b32_e32 v81, v2
	v_mov_b32_e32 v86, v2
	v_mov_b32_e32 v87, v2
	v_mov_b32_e32 v88, v2
	v_mov_b32_e32 v89, v2
	v_mov_b32_e32 v94, v2
	v_mov_b32_e32 v95, v2
	v_mov_b32_e32 v96, v2
	v_mov_b32_e32 v97, v2
	v_mov_b32_e32 v102, v2
	v_mov_b32_e32 v103, v2
	v_mov_b32_e32 v104, v2
	v_mov_b32_e32 v105, v2
	v_mov_b32_e32 v110, v2
	v_mov_b32_e32 v111, v2
	v_mov_b32_e32 v112, v2
	v_mov_b32_e32 v113, v2
	v_mov_b32_e32 v118, v2
	v_mov_b32_e32 v119, v2
	v_mov_b32_e32 v120, v2
	v_mov_b32_e32 v121, v2
	v_mov_b32_e32 v126, v2
	v_mov_b32_e32 v127, v2
	v_mov_b32_e32 v128, v2
	v_mov_b32_e32 v129, v2
	s_and_b64 vcc, exec, s[30:31]
	s_cbranch_vccnz .Lprio_skip_1
	s_setprio 1
.Lprio_skip_1:
.LBB0_416:
	v_or_b32_e32 v140, 0x10000, v146
	v_add_u32_e32 v148, 0x10400, v146
	ds_read_b128 v[140:143], v140
	ds_read_b128 v[160:163], v148
	v_add_u32_e32 v148, 0x10800, v146
	v_add_u32_e32 v149, 0x10c00, v146
	ds_read_b128 v[164:167], v148
	ds_read_b128 v[168:171], v149
	v_or_b32_e32 v148, 0x14000, v146
	v_add_u32_e32 v149, 0x14400, v146
	ds_read_b128 v[172:175], v148
	ds_read_b128 v[176:179], v149
	v_add_u32_e32 v148, 0x14800, v146
	s_add_i32 s51, s12, 2
	v_add_u32_e32 v149, 0x14c00, v146
	ds_read_b128 v[180:183], v148
	ds_read_b128 v[206:209], v149
	s_add_u32 s59, s18, 0x80
	s_addc_u32 s13, s19, 0
	s_cmp_eq_u32 s50, s12
	s_cselect_b32 s12, s40, s59
	s_cselect_b32 s13, s41, s13
	s_cselect_b32 s69, s43, s29
	s_cselect_b32 s68, s42, s28
	v_lshl_add_u64 v[148:149], s[18:19], 0, v[136:137]
	s_add_i32 m0, s3, 0xc000
	ds_read_b128 v[210:213], v145
	ds_read_b128 v[214:217], v145 offset:1024
	ds_read_b128 v[218:221], v145 offset:2048
	ds_read_b128 v[222:225], v145 offset:3072
	ds_read_b128 v[226:229], v145 offset:4096
	ds_read_b128 v[230:233], v145 offset:5120
	ds_read_b128 v[234:237], v145 offset:6144
	ds_read_b128 v[238:241], v145 offset:7168
	global_load_lds_dwordx4 v[148:149], off
	v_lshl_add_u64 v[148:149], s[18:19], 0, v[138:139]
	s_add_i32 m0, s3, 0xe000
	s_nop 0
	global_load_lds_dwordx4 v[148:149], off
	s_waitcnt vmcnt(8)
	s_waitcnt lgkmcnt(0)
	s_barrier
; #define PG8_STAGE(bufoff, gbase, voff) do { _Pragma("unroll") for (int _i = 0; _i < 2; ++_i) \
;         __builtin_amdgcn_global_load_lds((const unsigned*)((const char*)(gbase) + (voff)[_i]), (PG8_LAS unsigned*)(lds + (bufoff) + ldsw + _i * 8192), 16, 0, 0); } while (0)
; #define PG8_LDA(dst, b, h) do { _Pragma("unroll") for (int m = 0; m < 4; ++m) _Pragma("unroll") for (int k = 0; k < 2; ++k) dst[m][k] = *(const PG8_LAS bf16x8*)(lds + PG8_SA(b, h) + aoff + m * 2048 + k * 1024); } while (0)
; #define PG8_MMA(ai, bj, At, Bt) do { __builtin_amdgcn_s_setprio(1); _Pragma("unroll") for (int m = 0; m < 4; ++m) _Pragma("unroll") for (int n = 0; n < 2; ++n) _Pragma("unroll") for (int k = 0; k < 2; ++k) \
;         acc[ai][bj][m][n] = __builtin_amdgcn_mfma_f32_16x16x32_bf16(Bt[n][k], At[m][k], acc[ai][bj][m][n], 0, 0, 0); __builtin_amdgcn_s_setprio(0); } while (0)
; #define PG8_WAIT_V(n) asm volatile("s_waitcnt vmcnt(" #n ")" ::: "memory")
; #define PG8_WAIT_L(n) asm volatile("s_waitcnt lgkmcnt(" #n ")" ::: "memory")
; #define PG8_BAR __builtin_amdgcn_s_barrier()
; #define PG8_SCHED __builtin_amdgcn_sched_barrier(0)
; template <class Epi, class Sched, bool ALIGN_EPI = false, bool SP2 = false>
; __device__ __forceinline__ void gemm_phase(PG8_LAS unsigned char* lds, const Gemm g, const Sched& S, const Epi& E) {
;     ...
;             PG8_WAIT_V(8); PG8_WAIT_L(0); PG8_BAR; PG8_MMA(0, 0, At, B0); PG8_MMA(0, 1, At, B1); PG8_BAR; PG8_SCHED;
;             PG8_LDA(At, 0, 1); PG8_STAGE(PG8_SB(0, 0), b2, voffB); PG8_STAGE(PG8_SB(0, 1), b2 + hstep, voffB); PG8_STAGE(PG8_SA(0, 0), a2, voffA);
;             PG8_WAIT_V(8); PG8_WAIT_L(0); PG8_BAR; PG8_MMA(1, 0, At, B0); PG8_MMA(1, 1, At, B1); PG8_BAR; PG8_SCHED;
	s_waitcnt lgkmcnt(0)
	v_mfma_f32_16x16x32_bf16 v[126:129], v[140:143], v[210:213], v[126:129]
	v_mfma_f32_16x16x32_bf16 v[118:121], v[164:167], v[210:213], v[118:121]
	v_mfma_f32_16x16x32_bf16 v[110:113], v[140:143], v[218:221], v[110:113]
	v_mfma_f32_16x16x32_bf16 v[102:105], v[164:167], v[218:221], v[102:105]
	v_mfma_f32_16x16x32_bf16 v[94:97], v[140:143], v[226:229], v[94:97]
	v_mfma_f32_16x16x32_bf16 v[86:89], v[164:167], v[226:229], v[86:89]
	v_mfma_f32_16x16x32_bf16 v[78:81], v[140:143], v[234:237], v[78:81]
	v_mfma_f32_16x16x32_bf16 v[70:73], v[164:167], v[234:237], v[70:73]
	v_mfma_f32_16x16x32_bf16 v[126:129], v[160:163], v[214:217], v[126:129]
	v_mfma_f32_16x16x32_bf16 v[118:121], v[168:171], v[214:217], v[118:121]
	v_mfma_f32_16x16x32_bf16 v[110:113], v[160:163], v[222:225], v[110:113]
	v_mfma_f32_16x16x32_bf16 v[102:105], v[168:171], v[222:225], v[102:105]
	v_mfma_f32_16x16x32_bf16 v[94:97], v[160:163], v[230:233], v[94:97]
	v_mfma_f32_16x16x32_bf16 v[86:89], v[168:171], v[230:233], v[86:89]
	v_mfma_f32_16x16x32_bf16 v[78:81], v[160:163], v[238:241], v[78:81]
	v_mfma_f32_16x16x32_bf16 v[70:73], v[168:171], v[238:241], v[70:73]
	v_mfma_f32_16x16x32_bf16 v[122:125], v[172:175], v[210:213], v[122:125]
	v_mfma_f32_16x16x32_bf16 v[114:117], v[180:183], v[210:213], v[114:117]
	v_mfma_f32_16x16x32_bf16 v[106:109], v[172:175], v[218:221], v[106:109]
	v_mfma_f32_16x16x32_bf16 v[98:101], v[180:183], v[218:221], v[98:101]
	v_mfma_f32_16x16x32_bf16 v[90:93], v[172:175], v[226:229], v[90:93]
	v_mfma_f32_16x16x32_bf16 v[82:85], v[180:183], v[226:229], v[82:85]
	v_mfma_f32_16x16x32_bf16 v[74:77], v[172:175], v[234:237], v[74:77]
	v_mfma_f32_16x16x32_bf16 v[66:69], v[180:183], v[234:237], v[66:69]
	v_mfma_f32_16x16x32_bf16 v[122:125], v[176:179], v[214:217], v[122:125]
	v_mfma_f32_16x16x32_bf16 v[114:117], v[206:209], v[214:217], v[114:117]
	v_mfma_f32_16x16x32_bf16 v[106:109], v[176:179], v[222:225], v[106:109]
	v_mfma_f32_16x16x32_bf16 v[98:101], v[206:209], v[222:225], v[98:101]
	v_mfma_f32_16x16x32_bf16 v[90:93], v[176:179], v[230:233], v[90:93]
	v_mfma_f32_16x16x32_bf16 v[82:85], v[206:209], v[230:233], v[82:85]
	v_mfma_f32_16x16x32_bf16 v[74:77], v[176:179], v[238:241], v[74:77]
	v_mfma_f32_16x16x32_bf16 v[66:69], v[206:209], v[238:241], v[66:69]
	s_barrier
	s_mov_b32 m0, s16
	v_lshl_add_u64 v[148:149], s[68:69], 0, v[0:1]
	v_lshl_add_u64 v[156:157], s[68:69], 0, v[130:131]
	s_add_u32 s68, s68, s54
	ds_read_b128 v[210:213], v145 offset:16384
	ds_read_b128 v[214:217], v145 offset:17408
	ds_read_b128 v[218:221], v145 offset:18432
	ds_read_b128 v[222:225], v145 offset:19456
	ds_read_b128 v[226:229], v145 offset:20480
	ds_read_b128 v[230:233], v145 offset:21504
	ds_read_b128 v[234:237], v145 offset:22528
	ds_read_b128 v[238:241], v145 offset:23552
	global_load_lds_dwordx4 v[148:149], off
	s_mov_b32 m0, s17
	s_addc_u32 s69, s69, 0
	global_load_lds_dwordx4 v[156:157], off
	v_lshl_add_u64 v[192:193], s[68:69], 0, v[0:1]
	s_mov_b32 m0, s33
	v_lshl_add_u64 v[194:195], s[68:69], 0, v[130:131]
	global_load_lds_dwordx4 v[192:193], off
	s_mov_b32 m0, s34
	v_lshl_add_u64 v[242:243], s[12:13], 0, v[134:135]
	global_load_lds_dwordx4 v[194:195], off
	s_mov_b32 m0, s3
	v_lshl_add_u64 v[244:245], s[12:13], 0, v[132:133]
	global_load_lds_dwordx4 v[242:243], off
	s_mov_b32 m0, s36
	s_nop 0
	global_load_lds_dwordx4 v[244:245], off
	s_waitcnt vmcnt(8)
	s_waitcnt lgkmcnt(0)
	s_barrier
	s_waitcnt lgkmcnt(0)
	v_mfma_f32_16x16x32_bf16 v[62:65], v[140:143], v[210:213], v[62:65]
	v_mfma_f32_16x16x32_bf16 v[54:57], v[164:167], v[210:213], v[54:57]
	v_mfma_f32_16x16x32_bf16 v[46:49], v[140:143], v[218:221], v[46:49]
	v_mfma_f32_16x16x32_bf16 v[38:41], v[164:167], v[218:221], v[38:41]
	v_mfma_f32_16x16x32_bf16 v[30:33], v[140:143], v[226:229], v[30:33]
	v_mfma_f32_16x16x32_bf16 v[22:25], v[164:167], v[226:229], v[22:25]
	v_mfma_f32_16x16x32_bf16 v[14:17], v[140:143], v[234:237], v[14:17]
	v_mfma_f32_16x16x32_bf16 v[6:9], v[164:167], v[234:237], v[6:9]
	v_mfma_f32_16x16x32_bf16 v[62:65], v[160:163], v[214:217], v[62:65]
	v_mfma_f32_16x16x32_bf16 v[54:57], v[168:171], v[214:217], v[54:57]
	v_mfma_f32_16x16x32_bf16 v[46:49], v[160:163], v[222:225], v[46:49]
	v_mfma_f32_16x16x32_bf16 v[38:41], v[168:171], v[222:225], v[38:41]
	v_mfma_f32_16x16x32_bf16 v[30:33], v[160:163], v[230:233], v[30:33]
	v_mfma_f32_16x16x32_bf16 v[22:25], v[168:171], v[230:233], v[22:25]
	v_mfma_f32_16x16x32_bf16 v[14:17], v[160:163], v[238:241], v[14:17]
	v_mfma_f32_16x16x32_bf16 v[6:9], v[168:171], v[238:241], v[6:9]
	v_mfma_f32_16x16x32_bf16 v[58:61], v[172:175], v[210:213], v[58:61]
	v_mfma_f32_16x16x32_bf16 v[50:53], v[180:183], v[210:213], v[50:53]
	v_mfma_f32_16x16x32_bf16 v[42:45], v[172:175], v[218:221], v[42:45]
	v_mfma_f32_16x16x32_bf16 v[34:37], v[180:183], v[218:221], v[34:37]
	v_mfma_f32_16x16x32_bf16 v[26:29], v[172:175], v[226:229], v[26:29]
	v_mfma_f32_16x16x32_bf16 v[18:21], v[180:183], v[226:229], v[18:21]
	v_mfma_f32_16x16x32_bf16 v[10:13], v[172:175], v[234:237], v[10:13]
	v_mfma_f32_16x16x32_bf16 v[2:5], v[180:183], v[234:237], v[2:5]
	v_mfma_f32_16x16x32_bf16 v[58:61], v[176:179], v[214:217], v[58:61]
	v_mfma_f32_16x16x32_bf16 v[50:53], v[206:209], v[214:217], v[50:53]
	v_mfma_f32_16x16x32_bf16 v[42:45], v[176:179], v[222:225], v[42:45]
	v_mfma_f32_16x16x32_bf16 v[34:37], v[206:209], v[222:225], v[34:37]
	v_mfma_f32_16x16x32_bf16 v[26:29], v[176:179], v[230:233], v[26:29]
	v_mfma_f32_16x16x32_bf16 v[18:21], v[206:209], v[230:233], v[18:21]
	v_mfma_f32_16x16x32_bf16 v[10:13], v[176:179], v[238:241], v[10:13]
	v_mfma_f32_16x16x32_bf16 v[2:5], v[206:209], v[238:241], v[2:5]
	s_barrier
; #define PG8_STAGE(bufoff, gbase, voff) do { _Pragma("unroll") for (int _i = 0; _i < 2; ++_i) \
;         __builtin_amdgcn_global_load_lds((const unsigned*)((const char*)(gbase) + (voff)[_i]), (PG8_LAS unsigned*)(lds + (bufoff) + ldsw + _i * 8192), 16, 0, 0); } while (0)
; #define PG8_LDA(dst, b, h) do { _Pragma("unroll") for (int m = 0; m < 4; ++m) _Pragma("unroll") for (int k = 0; k < 2; ++k) dst[m][k] = *(const PG8_LAS bf16x8*)(lds + PG8_SA(b, h) + aoff + m * 2048 + k * 1024); } while (0)
; #define PG8_LDB(dst, b, h) do { _Pragma("unroll") for (int n = 0; n < 2; ++n) _Pragma("unroll") for (int k = 0; k < 2; ++k) dst[n][k] = *(const PG8_LAS bf16x8*)(lds + PG8_SB(b, h) + boff + n * 2048 + k * 1024); } while (0)
; #define PG8_MMA(ai, bj, At, Bt) do { __builtin_amdgcn_s_setprio(1); _Pragma("unroll") for (int m = 0; m < 4; ++m) _Pragma("unroll") for (int n = 0; n < 2; ++n) _Pragma("unroll") for (int k = 0; k < 2; ++k) \
;         acc[ai][bj][m][n] = __builtin_amdgcn_mfma_f32_16x16x32_bf16(Bt[n][k], At[m][k], acc[ai][bj][m][n], 0, 0, 0); __builtin_amdgcn_s_setprio(0); } while (0)
; #define PG8_WAIT_V(n) asm volatile("s_waitcnt vmcnt(" #n ")" ::: "memory")
; #define PG8_WAIT_L(n) asm volatile("s_waitcnt lgkmcnt(" #n ")" ::: "memory")
; #define PG8_BAR __builtin_amdgcn_s_barrier()
; #define PG8_SCHED __builtin_amdgcn_sched_barrier(0)
; template <class Epi, class Sched, bool ALIGN_EPI = false, bool SP2 = false>
; __device__ __forceinline__ void gemm_phase(PG8_LAS unsigned char* lds, const Gemm g, const Sched& S, const Epi& E) {
;     ...
;             PG8_LDB(B0, 1, 0); PG8_LDB(B1, 1, 1); PG8_SCHED; PG8_LDA(At, 1, 0); PG8_STAGE(PG8_SA(0, 1), a2 + hstep, voffA);
;             PG8_WAIT_V(8); PG8_WAIT_L(0); PG8_BAR; PG8_MMA(0, 0, At, B0); PG8_MMA(0, 1, At, B1); PG8_BAR; PG8_SCHED;
	v_or_b32_e32 v140, 0x18000, v146
	v_add_u32_e32 v158, 0x18400, v146
	ds_read_b128 v[140:143], v140
	ds_read_b128 v[160:163], v158
	v_add_u32_e32 v158, 0x18800, v146
	v_add_u32_e32 v168, 0x18c00, v146
	ds_read_b128 v[164:167], v158
	ds_read_b128 v[168:171], v168
	v_or_b32_e32 v158, 0x1c000, v146
	v_add_u32_e32 v176, 0x1c400, v146
	ds_read_b128 v[172:175], v158
	ds_read_b128 v[176:179], v176
	v_add_u32_e32 v158, 0x1c800, v146
	v_add_u32_e32 v205, 0x1cc00, v146
	ds_read_b128 v[180:183], v158
	ds_read_b128 v[206:209], v205
	s_add_u32 s12, s12, s54
	s_addc_u32 s13, s13, 0
	s_mov_b32 m0, s37
	v_lshl_add_u64 v[246:247], s[12:13], 0, v[134:135]
	ds_read_b128 v[210:213], v145 offset:32768
	ds_read_b128 v[214:217], v145 offset:33792
	ds_read_b128 v[218:221], v145 offset:34816
	ds_read_b128 v[222:225], v145 offset:35840
	ds_read_b128 v[226:229], v145 offset:36864
	ds_read_b128 v[230:233], v145 offset:37888
	ds_read_b128 v[234:237], v145 offset:38912
	ds_read_b128 v[238:241], v145 offset:39936
	global_load_lds_dwordx4 v[246:247], off
	v_lshl_add_u64 v[246:247], s[12:13], 0, v[132:133]
	s_mov_b32 m0, s44
	s_nop 0
	global_load_lds_dwordx4 v[246:247], off
	s_waitcnt vmcnt(8)
	s_waitcnt lgkmcnt(0)
	s_barrier
	s_waitcnt lgkmcnt(0)
	v_mfma_f32_16x16x32_bf16 v[126:129], v[140:143], v[210:213], v[126:129]
	v_mfma_f32_16x16x32_bf16 v[118:121], v[164:167], v[210:213], v[118:121]
	v_mfma_f32_16x16x32_bf16 v[110:113], v[140:143], v[218:221], v[110:113]
	v_mfma_f32_16x16x32_bf16 v[102:105], v[164:167], v[218:221], v[102:105]
	v_mfma_f32_16x16x32_bf16 v[94:97], v[140:143], v[226:229], v[94:97]
	v_mfma_f32_16x16x32_bf16 v[86:89], v[164:167], v[226:229], v[86:89]
	v_mfma_f32_16x16x32_bf16 v[78:81], v[140:143], v[234:237], v[78:81]
	v_mfma_f32_16x16x32_bf16 v[70:73], v[164:167], v[234:237], v[70:73]
	v_mfma_f32_16x16x32_bf16 v[126:129], v[160:163], v[214:217], v[126:129]
	v_mfma_f32_16x16x32_bf16 v[118:121], v[168:171], v[214:217], v[118:121]
	v_mfma_f32_16x16x32_bf16 v[110:113], v[160:163], v[222:225], v[110:113]
	v_mfma_f32_16x16x32_bf16 v[102:105], v[168:171], v[222:225], v[102:105]
	v_mfma_f32_16x16x32_bf16 v[94:97], v[160:163], v[230:233], v[94:97]
	v_mfma_f32_16x16x32_bf16 v[86:89], v[168:171], v[230:233], v[86:89]
	v_mfma_f32_16x16x32_bf16 v[78:81], v[160:163], v[238:241], v[78:81]
	v_mfma_f32_16x16x32_bf16 v[70:73], v[168:171], v[238:241], v[70:73]
	v_mfma_f32_16x16x32_bf16 v[122:125], v[172:175], v[210:213], v[122:125]
	v_mfma_f32_16x16x32_bf16 v[114:117], v[180:183], v[210:213], v[114:117]
	v_mfma_f32_16x16x32_bf16 v[106:109], v[172:175], v[218:221], v[106:109]
	v_mfma_f32_16x16x32_bf16 v[98:101], v[180:183], v[218:221], v[98:101]
	v_mfma_f32_16x16x32_bf16 v[90:93], v[172:175], v[226:229], v[90:93]
	v_mfma_f32_16x16x32_bf16 v[82:85], v[180:183], v[226:229], v[82:85]
	v_mfma_f32_16x16x32_bf16 v[74:77], v[172:175], v[234:237], v[74:77]
	v_mfma_f32_16x16x32_bf16 v[66:69], v[180:183], v[234:237], v[66:69]
	v_mfma_f32_16x16x32_bf16 v[122:125], v[176:179], v[214:217], v[122:125]
	v_mfma_f32_16x16x32_bf16 v[114:117], v[206:209], v[214:217], v[114:117]
	v_mfma_f32_16x16x32_bf16 v[106:109], v[176:179], v[222:225], v[106:109]
	v_mfma_f32_16x16x32_bf16 v[98:101], v[206:209], v[222:225], v[98:101]
	v_mfma_f32_16x16x32_bf16 v[90:93], v[176:179], v[230:233], v[90:93]
	v_mfma_f32_16x16x32_bf16 v[82:85], v[206:209], v[230:233], v[82:85]
	v_mfma_f32_16x16x32_bf16 v[74:77], v[176:179], v[238:241], v[74:77]
	v_mfma_f32_16x16x32_bf16 v[66:69], v[206:209], v[238:241], v[66:69]
	s_barrier
; #define PG8_STAGE(bufoff, gbase, voff) do { _Pragma("unroll") for (int _i = 0; _i < 2; ++_i) \
;         __builtin_amdgcn_global_load_lds((const unsigned*)((const char*)(gbase) + (voff)[_i]), (PG8_LAS unsigned*)(lds + (bufoff) + ldsw + _i * 8192), 16, 0, 0); } while (0)
; #define PG8_LDA(dst, b, h) do { _Pragma("unroll") for (int m = 0; m < 4; ++m) _Pragma("unroll") for (int k = 0; k < 2; ++k) dst[m][k] = *(const PG8_LAS bf16x8*)(lds + PG8_SA(b, h) + aoff + m * 2048 + k * 1024); } while (0)
; #define PG8_MMA(ai, bj, At, Bt) do { __builtin_amdgcn_s_setprio(1); _Pragma("unroll") for (int m = 0; m < 4; ++m) _Pragma("unroll") for (int n = 0; n < 2; ++n) _Pragma("unroll") for (int k = 0; k < 2; ++k) \
;         acc[ai][bj][m][n] = __builtin_amdgcn_mfma_f32_16x16x32_bf16(Bt[n][k], At[m][k], acc[ai][bj][m][n], 0, 0, 0); __builtin_amdgcn_s_setprio(0); } while (0)
; #define PG8_WAIT_V(n) asm volatile("s_waitcnt vmcnt(" #n ")" ::: "memory")
; #define PG8_WAIT_L(n) asm volatile("s_waitcnt lgkmcnt(" #n ")" ::: "memory")
; #define PG8_BAR __builtin_amdgcn_s_barrier()
; #define PG8_SCHED __builtin_amdgcn_sched_barrier(0)
; template <class Epi, class Sched, bool ALIGN_EPI = false, bool SP2 = false>
; __device__ __forceinline__ void gemm_phase(PG8_LAS unsigned char* lds, const Gemm g, const Sched& S, const Epi& E) {
;     ...
;         for (int t = 0; t < nt; t += 2) {
;     ...
;             PG8_LDA(At, 1, 1); PG8_STAGE(PG8_SB(1, 0), b3, voffB); PG8_STAGE(PG8_SB(1, 1), b3 + hstep, voffB); PG8_STAGE(PG8_SA(1, 0), a3, voffA);
;             PG8_WAIT_V(8); PG8_WAIT_L(0); PG8_BAR; PG8_MMA(1, 0, At, B0); PG8_MMA(1, 1, At, B1); PG8_BAR; PG8_SCHED;
	s_mov_b32 m0, s45
	v_lshl_add_u64 v[148:149], v[148:149], 0, s[60:61]
	ds_read_b128 v[210:213], v145 offset:49152
	ds_read_b128 v[214:217], v145 offset:50176
	ds_read_b128 v[218:221], v145 offset:51200
	ds_read_b128 v[222:225], v145 offset:52224
	ds_read_b128 v[226:229], v145 offset:53248
	ds_read_b128 v[230:233], v145 offset:54272
	ds_read_b128 v[234:237], v145 offset:55296
	ds_read_b128 v[238:241], v145 offset:56320
	global_load_lds_dwordx4 v[148:149], off
	v_lshl_add_u64 v[148:149], v[156:157], 0, s[60:61]
	s_mov_b32 m0, s46
	s_nop 0
	global_load_lds_dwordx4 v[148:149], off
	v_lshl_add_u64 v[148:149], v[192:193], 0, s[60:61]
	s_mov_b32 m0, s49
	s_nop 0
	global_load_lds_dwordx4 v[148:149], off
	v_lshl_add_u64 v[148:149], v[194:195], 0, s[60:61]
	s_mov_b32 m0, s52
	s_nop 0
	global_load_lds_dwordx4 v[148:149], off
	v_lshl_add_u64 v[148:149], v[242:243], 0, s[60:61]
	s_mov_b32 m0, s47
	s_nop 0
	global_load_lds_dwordx4 v[148:149], off
	v_lshl_add_u64 v[148:149], v[244:245], 0, s[60:61]
	s_mov_b32 m0, s48
	s_nop 0
	global_load_lds_dwordx4 v[148:149], off
	s_waitcnt vmcnt(8)
	s_waitcnt lgkmcnt(0)
	s_barrier
	s_waitcnt lgkmcnt(0)
	v_mfma_f32_16x16x32_bf16 v[62:65], v[140:143], v[210:213], v[62:65]
	v_mfma_f32_16x16x32_bf16 v[54:57], v[164:167], v[210:213], v[54:57]
	v_mfma_f32_16x16x32_bf16 v[46:49], v[140:143], v[218:221], v[46:49]
	v_mfma_f32_16x16x32_bf16 v[38:41], v[164:167], v[218:221], v[38:41]
	v_mfma_f32_16x16x32_bf16 v[30:33], v[140:143], v[226:229], v[30:33]
	v_mfma_f32_16x16x32_bf16 v[22:25], v[164:167], v[226:229], v[22:25]
	v_mfma_f32_16x16x32_bf16 v[14:17], v[140:143], v[234:237], v[14:17]
	v_mfma_f32_16x16x32_bf16 v[6:9], v[164:167], v[234:237], v[6:9]
	v_mfma_f32_16x16x32_bf16 v[62:65], v[160:163], v[214:217], v[62:65]
	v_mfma_f32_16x16x32_bf16 v[54:57], v[168:171], v[214:217], v[54:57]
	v_mfma_f32_16x16x32_bf16 v[46:49], v[160:163], v[222:225], v[46:49]
	v_mfma_f32_16x16x32_bf16 v[38:41], v[168:171], v[222:225], v[38:41]
	v_mfma_f32_16x16x32_bf16 v[30:33], v[160:163], v[230:233], v[30:33]
	v_mfma_f32_16x16x32_bf16 v[22:25], v[168:171], v[230:233], v[22:25]
	v_mfma_f32_16x16x32_bf16 v[14:17], v[160:163], v[238:241], v[14:17]
	v_mfma_f32_16x16x32_bf16 v[6:9], v[168:171], v[238:241], v[6:9]
	v_mfma_f32_16x16x32_bf16 v[58:61], v[172:175], v[210:213], v[58:61]
	v_mfma_f32_16x16x32_bf16 v[50:53], v[180:183], v[210:213], v[50:53]
	v_mfma_f32_16x16x32_bf16 v[42:45], v[172:175], v[218:221], v[42:45]
	v_mfma_f32_16x16x32_bf16 v[34:37], v[180:183], v[218:221], v[34:37]
	v_mfma_f32_16x16x32_bf16 v[26:29], v[172:175], v[226:229], v[26:29]
	v_mfma_f32_16x16x32_bf16 v[18:21], v[180:183], v[226:229], v[18:21]
	v_mfma_f32_16x16x32_bf16 v[10:13], v[172:175], v[234:237], v[10:13]
	v_mfma_f32_16x16x32_bf16 v[2:5], v[180:183], v[234:237], v[2:5]
	v_mfma_f32_16x16x32_bf16 v[58:61], v[176:179], v[214:217], v[58:61]
	v_mfma_f32_16x16x32_bf16 v[50:53], v[206:209], v[214:217], v[50:53]
	v_mfma_f32_16x16x32_bf16 v[42:45], v[176:179], v[222:225], v[42:45]
	v_mfma_f32_16x16x32_bf16 v[34:37], v[206:209], v[222:225], v[34:37]
	v_mfma_f32_16x16x32_bf16 v[26:29], v[176:179], v[230:233], v[26:29]
	v_mfma_f32_16x16x32_bf16 v[18:21], v[206:209], v[230:233], v[18:21]
	v_mfma_f32_16x16x32_bf16 v[10:13], v[176:179], v[238:241], v[10:13]
	v_mfma_f32_16x16x32_bf16 v[2:5], v[206:209], v[238:241], v[2:5]
	s_barrier
	s_add_u32 s18, s18, 0x100
	s_addc_u32 s19, s19, 0
	s_add_u32 s28, s28, 0x100
	s_addc_u32 s29, s29, 0
	s_cmp_ge_i32 s51, s63
	s_mov_b32 s12, s51
	s_cbranch_scc0 .LBB0_416
	s_setprio 0
	v_readlane_b32 s68, v253, 55
	v_readlane_b32 s69, v253, 56
	s_and_b64 vcc, exec, s[30:31]
	s_cbranch_vccz .LBB0_419

; #define PG8_STAGE(bufoff, gbase, voff) do { _Pragma("unroll") for (int _i = 0; _i < 2; ++_i) \
;         __builtin_amdgcn_global_load_lds((const unsigned*)((const char*)(gbase) + (voff)[_i]), (PG8_LAS unsigned*)(lds + (bufoff) + ldsw + _i * 8192), 16, 0, 0); } while (0)
; #define PG8_LDA(dst, b, h) do { _Pragma("unroll") for (int m = 0; m < 4; ++m) _Pragma("unroll") for (int k = 0; k < 2; ++k) dst[m][k] = *(const PG8_LAS bf16x8*)(lds + PG8_SA(b, h) + aoff + m * 2048 + k * 1024); } while (0)
; #define PG8_LDB(dst, b, h) do { _Pragma("unroll") for (int n = 0; n < 2; ++n) _Pragma("unroll") for (int k = 0; k < 2; ++k) dst[n][k] = *(const PG8_LAS bf16x8*)(lds + PG8_SB(b, h) + boff + n * 2048 + k * 1024); } while (0)
; #define PG8_MMA(ai, bj, At, Bt) do { __builtin_amdgcn_s_setprio(1); _Pragma("unroll") for (int m = 0; m < 4; ++m) _Pragma("unroll") for (int n = 0; n < 2; ++n) _Pragma("unroll") for (int k = 0; k < 2; ++k) \
;         acc[ai][bj][m][n] = __builtin_amdgcn_mfma_f32_16x16x32_bf16(Bt[n][k], At[m][k], acc[ai][bj][m][n], 0, 0, 0); __builtin_amdgcn_s_setprio(0); } while (0)
; #define PG8_WAIT_V(n) asm volatile("s_waitcnt vmcnt(" #n ")" ::: "memory")
; #define PG8_WAIT_L(n) asm volatile("s_waitcnt lgkmcnt(" #n ")" ::: "memory")
; #define PG8_BAR __builtin_amdgcn_s_barrier()
; #define PG8_SCHED __builtin_amdgcn_sched_barrier(0)
; template <class Epi, class Sched, bool ALIGN_EPI = false, bool SP2 = false>
; __device__ __forceinline__ void gemm_phase(PG8_LAS unsigned char* lds, const Gemm g, const Sched& S, const Epi& E) {
;     ...
;             PG8_LDB(B0, 0, 0); PG8_LDB(B1, 0, 1); PG8_SCHED; PG8_LDA(At, 0, 0); PG8_STAGE(PG8_SA(1, 1), a1 + hstep, voffA);
;             PG8_WAIT_V(8); PG8_WAIT_L(0); PG8_BAR; PG8_MMA(0, 0, At, B0); PG8_MMA(0, 1, At, B1); PG8_BAR; PG8_SCHED;
;     ...
; #pragma unroll
;         for (int a = 0; a < 2; ++a)
; #pragma unroll
;             for (int b = 0; b < 2; ++b)
; #pragma unroll
;                 for (int m = 0; m < 4; ++m)
; #pragma unroll
;                     for (int n = 0; n < 2; ++n) acc[a][b][m][n] = (f32x4){0.f, 0.f, 0.f, 0.f};
.LBB0_455:
	s_add_i32 s19, s48, -2
	s_add_u32 s44, s44, 0x80
	s_addc_u32 s45, s45, 0
	s_add_u32 s69, s12, 0x100
	v_mov_b32_e32 v2, 0
	s_addc_u32 s72, s13, 0
	s_mov_b32 s12, 0
	v_mov_b32_e32 v3, v2
	v_mov_b32_e32 v4, v2
	v_mov_b32_e32 v5, v2
	v_mov_b32_e32 v6, v2
	v_mov_b32_e32 v7, v2
	v_mov_b32_e32 v8, v2
	v_mov_b32_e32 v9, v2
	v_mov_b32_e32 v18, v2
	v_mov_b32_e32 v19, v2
	v_mov_b32_e32 v20, v2
	v_mov_b32_e32 v21, v2
	v_mov_b32_e32 v22, v2
	v_mov_b32_e32 v23, v2
	v_mov_b32_e32 v24, v2
	v_mov_b32_e32 v25, v2
	v_mov_b32_e32 v34, v2
	v_mov_b32_e32 v35, v2
	v_mov_b32_e32 v36, v2
	v_mov_b32_e32 v37, v2
	v_mov_b32_e32 v38, v2
	v_mov_b32_e32 v39, v2
	v_mov_b32_e32 v40, v2
	v_mov_b32_e32 v41, v2
	v_mov_b32_e32 v50, v2
	v_mov_b32_e32 v51, v2
	v_mov_b32_e32 v52, v2
	v_mov_b32_e32 v53, v2
	v_mov_b32_e32 v54, v2
	v_mov_b32_e32 v55, v2
	v_mov_b32_e32 v56, v2
	v_mov_b32_e32 v57, v2
	v_mov_b32_e32 v10, v2
	v_mov_b32_e32 v11, v2
	v_mov_b32_e32 v12, v2
	v_mov_b32_e32 v13, v2
	v_mov_b32_e32 v14, v2
	v_mov_b32_e32 v15, v2
	v_mov_b32_e32 v16, v2
	v_mov_b32_e32 v17, v2
	v_mov_b32_e32 v26, v2
	v_mov_b32_e32 v27, v2
	v_mov_b32_e32 v28, v2
	v_mov_b32_e32 v29, v2
	v_mov_b32_e32 v30, v2
	v_mov_b32_e32 v31, v2
	v_mov_b32_e32 v32, v2
	v_mov_b32_e32 v33, v2
	v_mov_b32_e32 v42, v2
	v_mov_b32_e32 v43, v2
	v_mov_b32_e32 v44, v2
	v_mov_b32_e32 v45, v2
	v_mov_b32_e32 v46, v2
	v_mov_b32_e32 v47, v2
	v_mov_b32_e32 v48, v2
	v_mov_b32_e32 v49, v2
	v_mov_b32_e32 v58, v2
	v_mov_b32_e32 v59, v2
	v_mov_b32_e32 v60, v2
	v_mov_b32_e32 v61, v2
	v_mov_b32_e32 v62, v2
	v_mov_b32_e32 v63, v2
	v_mov_b32_e32 v64, v2
	v_mov_b32_e32 v65, v2
	v_mov_b32_e32 v66, v2
	v_mov_b32_e32 v67, v2
	v_mov_b32_e32 v68, v2
	v_mov_b32_e32 v69, v2
	v_mov_b32_e32 v70, v2
	v_mov_b32_e32 v71, v2
	v_mov_b32_e32 v72, v2
	v_mov_b32_e32 v73, v2
	v_mov_b32_e32 v82, v2
	v_mov_b32_e32 v83, v2
	v_mov_b32_e32 v84, v2
	v_mov_b32_e32 v85, v2
	v_mov_b32_e32 v86, v2
	v_mov_b32_e32 v87, v2
	v_mov_b32_e32 v88, v2
	v_mov_b32_e32 v89, v2
	v_mov_b32_e32 v98, v2
	v_mov_b32_e32 v99, v2
	v_mov_b32_e32 v100, v2
	v_mov_b32_e32 v101, v2
	v_mov_b32_e32 v102, v2
	v_mov_b32_e32 v103, v2
	v_mov_b32_e32 v104, v2
	v_mov_b32_e32 v105, v2
	v_mov_b32_e32 v114, v2
	v_mov_b32_e32 v115, v2
	v_mov_b32_e32 v116, v2
	v_mov_b32_e32 v117, v2
	v_mov_b32_e32 v118, v2
	v_mov_b32_e32 v119, v2
	v_mov_b32_e32 v120, v2
	v_mov_b32_e32 v121, v2
	v_mov_b32_e32 v74, v2
	v_mov_b32_e32 v75, v2
	v_mov_b32_e32 v76, v2
	v_mov_b32_e32 v77, v2
	v_mov_b32_e32 v78, v2
	v_mov_b32_e32 v79, v2
	v_mov_b32_e32 v80, v2
	v_mov_b32_e32 v81, v2
	v_mov_b32_e32 v90, v2
	v_mov_b32_e32 v91, v2
	v_mov_b32_e32 v92, v2
	v_mov_b32_e32 v93, v2
	v_mov_b32_e32 v94, v2
	v_mov_b32_e32 v95, v2
	v_mov_b32_e32 v96, v2
	v_mov_b32_e32 v97, v2
	v_mov_b32_e32 v106, v2
	v_mov_b32_e32 v107, v2
	v_mov_b32_e32 v108, v2
	v_mov_b32_e32 v109, v2
	v_mov_b32_e32 v110, v2
	v_mov_b32_e32 v111, v2
	v_mov_b32_e32 v112, v2
	v_mov_b32_e32 v113, v2
	v_mov_b32_e32 v122, v2
	v_mov_b32_e32 v123, v2
	v_mov_b32_e32 v124, v2
	v_mov_b32_e32 v125, v2
	v_mov_b32_e32 v126, v2
	v_mov_b32_e32 v127, v2
	v_mov_b32_e32 v128, v2
	v_mov_b32_e32 v129, v2
	s_and_b64 vcc, exec, s[40:41]
	s_cbranch_vccnz .Lprio_skip_2
	s_setprio 1
.Lprio_skip_2:
.LBB0_456:
	v_or_b32_e32 v140, 0x10000, v145
	v_add_u32_e32 v142, 0x10400, v145
	ds_read_b128 v[160:163], v140
	ds_read_b128 v[164:167], v142
	v_add_u32_e32 v140, 0x10800, v145
	v_add_u32_e32 v142, 0x10c00, v145
	ds_read_b128 v[168:171], v140
	ds_read_b128 v[172:175], v142
	v_or_b32_e32 v140, 0x14000, v145
	v_add_u32_e32 v142, 0x14400, v145
	ds_read_b128 v[176:179], v140
	ds_read_b128 v[180:183], v142
	v_add_u32_e32 v140, 0x14800, v145
	s_add_i32 s73, s12, 2
	v_add_u32_e32 v142, 0x14c00, v145
	ds_read_b128 v[206:209], v140
	ds_read_b128 v[210:213], v142
	s_add_u32 s74, s44, 0x80
	s_addc_u32 s13, s45, 0
	s_cmp_eq_u32 s19, s12
	s_cselect_b32 s12, s28, s74
	s_cselect_b32 s13, s29, s13
	s_cselect_b32 s75, s43, s72
	s_cselect_b32 s74, s42, s69
	v_lshl_add_u64 v[142:143], s[44:45], 0, v[136:137]
	s_add_i32 m0, s15, 0xc000
	ds_read_b128 v[214:217], v144
	ds_read_b128 v[218:221], v144 offset:1024
	ds_read_b128 v[222:225], v144 offset:2048
	ds_read_b128 v[226:229], v144 offset:3072
	ds_read_b128 v[230:233], v144 offset:4096
	ds_read_b128 v[234:237], v144 offset:5120
	ds_read_b128 v[238:241], v144 offset:6144
	ds_read_b128 v[242:245], v144 offset:7168
	global_load_lds_dwordx4 v[142:143], off
	v_lshl_add_u64 v[142:143], s[44:45], 0, v[138:139]
	s_add_i32 m0, s15, 0xe000
	s_nop 0
	global_load_lds_dwordx4 v[142:143], off
	s_waitcnt vmcnt(8)
	s_waitcnt lgkmcnt(0)
	s_barrier
; #define PG8_STAGE(bufoff, gbase, voff) do { _Pragma("unroll") for (int _i = 0; _i < 2; ++_i) \
;         __builtin_amdgcn_global_load_lds((const unsigned*)((const char*)(gbase) + (voff)[_i]), (PG8_LAS unsigned*)(lds + (bufoff) + ldsw + _i * 8192), 16, 0, 0); } while (0)
; #define PG8_LDA(dst, b, h) do { _Pragma("unroll") for (int m = 0; m < 4; ++m) _Pragma("unroll") for (int k = 0; k < 2; ++k) dst[m][k] = *(const PG8_LAS bf16x8*)(lds + PG8_SA(b, h) + aoff + m * 2048 + k * 1024); } while (0)
; #define PG8_MMA(ai, bj, At, Bt) do { __builtin_amdgcn_s_setprio(1); _Pragma("unroll") for (int m = 0; m < 4; ++m) _Pragma("unroll") for (int n = 0; n < 2; ++n) _Pragma("unroll") for (int k = 0; k < 2; ++k) \
;         acc[ai][bj][m][n] = __builtin_amdgcn_mfma_f32_16x16x32_bf16(Bt[n][k], At[m][k], acc[ai][bj][m][n], 0, 0, 0); __builtin_amdgcn_s_setprio(0); } while (0)
; #define PG8_WAIT_V(n) asm volatile("s_waitcnt vmcnt(" #n ")" ::: "memory")
; #define PG8_WAIT_L(n) asm volatile("s_waitcnt lgkmcnt(" #n ")" ::: "memory")
; #define PG8_BAR __builtin_amdgcn_s_barrier()
; #define PG8_SCHED __builtin_amdgcn_sched_barrier(0)
; template <class Epi, class Sched, bool ALIGN_EPI = false, bool SP2 = false>
; __device__ __forceinline__ void gemm_phase(PG8_LAS unsigned char* lds, const Gemm g, const Sched& S, const Epi& E) {
;     ...
;             PG8_WAIT_V(8); PG8_WAIT_L(0); PG8_BAR; PG8_MMA(0, 0, At, B0); PG8_MMA(0, 1, At, B1); PG8_BAR; PG8_SCHED;
;             PG8_LDA(At, 0, 1); PG8_STAGE(PG8_SB(0, 0), b2, voffB); PG8_STAGE(PG8_SB(0, 1), b2 + hstep, voffB); PG8_STAGE(PG8_SA(0, 0), a2, voffA);
;             PG8_WAIT_V(8); PG8_WAIT_L(0); PG8_BAR; PG8_MMA(1, 0, At, B0); PG8_MMA(1, 1, At, B1); PG8_BAR; PG8_SCHED;
	s_waitcnt lgkmcnt(0)
	v_mfma_f32_16x16x32_bf16 v[126:129], v[160:163], v[214:217], v[126:129]
	v_mfma_f32_16x16x32_bf16 v[122:125], v[168:171], v[214:217], v[122:125]
	v_mfma_f32_16x16x32_bf16 v[110:113], v[160:163], v[222:225], v[110:113]
	v_mfma_f32_16x16x32_bf16 v[106:109], v[168:171], v[222:225], v[106:109]
	v_mfma_f32_16x16x32_bf16 v[94:97], v[160:163], v[230:233], v[94:97]
	v_mfma_f32_16x16x32_bf16 v[90:93], v[168:171], v[230:233], v[90:93]
	v_mfma_f32_16x16x32_bf16 v[78:81], v[160:163], v[238:241], v[78:81]
	v_mfma_f32_16x16x32_bf16 v[74:77], v[168:171], v[238:241], v[74:77]
	v_mfma_f32_16x16x32_bf16 v[126:129], v[164:167], v[218:221], v[126:129]
	v_mfma_f32_16x16x32_bf16 v[122:125], v[172:175], v[218:221], v[122:125]
	v_mfma_f32_16x16x32_bf16 v[110:113], v[164:167], v[226:229], v[110:113]
	v_mfma_f32_16x16x32_bf16 v[106:109], v[172:175], v[226:229], v[106:109]
	v_mfma_f32_16x16x32_bf16 v[94:97], v[164:167], v[234:237], v[94:97]
	v_mfma_f32_16x16x32_bf16 v[90:93], v[172:175], v[234:237], v[90:93]
	v_mfma_f32_16x16x32_bf16 v[78:81], v[164:167], v[242:245], v[78:81]
	v_mfma_f32_16x16x32_bf16 v[74:77], v[172:175], v[242:245], v[74:77]
	v_mfma_f32_16x16x32_bf16 v[118:121], v[176:179], v[214:217], v[118:121]
	v_mfma_f32_16x16x32_bf16 v[114:117], v[206:209], v[214:217], v[114:117]
	v_mfma_f32_16x16x32_bf16 v[102:105], v[176:179], v[222:225], v[102:105]
	v_mfma_f32_16x16x32_bf16 v[98:101], v[206:209], v[222:225], v[98:101]
	v_mfma_f32_16x16x32_bf16 v[86:89], v[176:179], v[230:233], v[86:89]
	v_mfma_f32_16x16x32_bf16 v[82:85], v[206:209], v[230:233], v[82:85]
	v_mfma_f32_16x16x32_bf16 v[70:73], v[176:179], v[238:241], v[70:73]
	v_mfma_f32_16x16x32_bf16 v[66:69], v[206:209], v[238:241], v[66:69]
	v_mfma_f32_16x16x32_bf16 v[118:121], v[180:183], v[218:221], v[118:121]
	v_mfma_f32_16x16x32_bf16 v[114:117], v[210:213], v[218:221], v[114:117]
	v_mfma_f32_16x16x32_bf16 v[102:105], v[180:183], v[226:229], v[102:105]
	v_mfma_f32_16x16x32_bf16 v[98:101], v[210:213], v[226:229], v[98:101]
	v_mfma_f32_16x16x32_bf16 v[86:89], v[180:183], v[234:237], v[86:89]
	v_mfma_f32_16x16x32_bf16 v[82:85], v[210:213], v[234:237], v[82:85]
	v_mfma_f32_16x16x32_bf16 v[70:73], v[180:183], v[242:245], v[70:73]
	v_mfma_f32_16x16x32_bf16 v[66:69], v[210:213], v[242:245], v[66:69]
	s_barrier
	s_mov_b32 m0, s16
	v_lshl_add_u64 v[142:143], s[74:75], 0, v[0:1]
	v_lshl_add_u64 v[148:149], s[74:75], 0, v[134:135]
	s_add_u32 s74, s74, s54
	ds_read_b128 v[214:217], v144 offset:16384
	ds_read_b128 v[218:221], v144 offset:17408
	ds_read_b128 v[222:225], v144 offset:18432
	ds_read_b128 v[226:229], v144 offset:19456
	ds_read_b128 v[230:233], v144 offset:20480
	ds_read_b128 v[234:237], v144 offset:21504
	ds_read_b128 v[238:241], v144 offset:22528
	ds_read_b128 v[242:245], v144 offset:23552
	global_load_lds_dwordx4 v[142:143], off
	s_mov_b32 m0, s17
	s_addc_u32 s75, s75, 0
	global_load_lds_dwordx4 v[148:149], off
	v_lshl_add_u64 v[156:157], s[74:75], 0, v[0:1]
	s_mov_b32 m0, s33
	v_lshl_add_u64 v[246:247], s[74:75], 0, v[134:135]
	global_load_lds_dwordx4 v[156:157], off
	s_mov_b32 m0, s36
	v_lshl_add_u64 v[248:249], s[12:13], 0, v[130:131]
	global_load_lds_dwordx4 v[246:247], off
	s_mov_b32 m0, s15
	v_lshl_add_u64 v[192:193], s[12:13], 0, v[132:133]
	global_load_lds_dwordx4 v[248:249], off
	s_mov_b32 m0, s37
	s_nop 0
	global_load_lds_dwordx4 v[192:193], off
	s_waitcnt vmcnt(8)
	s_waitcnt lgkmcnt(0)
	s_barrier
	s_waitcnt lgkmcnt(0)
	v_mfma_f32_16x16x32_bf16 v[62:65], v[160:163], v[214:217], v[62:65]
	v_mfma_f32_16x16x32_bf16 v[58:61], v[168:171], v[214:217], v[58:61]
	v_mfma_f32_16x16x32_bf16 v[46:49], v[160:163], v[222:225], v[46:49]
	v_mfma_f32_16x16x32_bf16 v[42:45], v[168:171], v[222:225], v[42:45]
	v_mfma_f32_16x16x32_bf16 v[30:33], v[160:163], v[230:233], v[30:33]
	v_mfma_f32_16x16x32_bf16 v[26:29], v[168:171], v[230:233], v[26:29]
	v_mfma_f32_16x16x32_bf16 v[14:17], v[160:163], v[238:241], v[14:17]
	v_mfma_f32_16x16x32_bf16 v[10:13], v[168:171], v[238:241], v[10:13]
	v_mfma_f32_16x16x32_bf16 v[62:65], v[164:167], v[218:221], v[62:65]
	v_mfma_f32_16x16x32_bf16 v[58:61], v[172:175], v[218:221], v[58:61]
	v_mfma_f32_16x16x32_bf16 v[46:49], v[164:167], v[226:229], v[46:49]
	v_mfma_f32_16x16x32_bf16 v[42:45], v[172:175], v[226:229], v[42:45]
	v_mfma_f32_16x16x32_bf16 v[30:33], v[164:167], v[234:237], v[30:33]
	v_mfma_f32_16x16x32_bf16 v[26:29], v[172:175], v[234:237], v[26:29]
	v_mfma_f32_16x16x32_bf16 v[14:17], v[164:167], v[242:245], v[14:17]
	v_mfma_f32_16x16x32_bf16 v[10:13], v[172:175], v[242:245], v[10:13]
	v_mfma_f32_16x16x32_bf16 v[54:57], v[176:179], v[214:217], v[54:57]
	v_mfma_f32_16x16x32_bf16 v[50:53], v[206:209], v[214:217], v[50:53]
	v_mfma_f32_16x16x32_bf16 v[38:41], v[176:179], v[222:225], v[38:41]
	v_mfma_f32_16x16x32_bf16 v[34:37], v[206:209], v[222:225], v[34:37]
	v_mfma_f32_16x16x32_bf16 v[22:25], v[176:179], v[230:233], v[22:25]
	v_mfma_f32_16x16x32_bf16 v[18:21], v[206:209], v[230:233], v[18:21]
	v_mfma_f32_16x16x32_bf16 v[6:9], v[176:179], v[238:241], v[6:9]
	v_mfma_f32_16x16x32_bf16 v[2:5], v[206:209], v[238:241], v[2:5]
	v_mfma_f32_16x16x32_bf16 v[54:57], v[180:183], v[218:221], v[54:57]
	v_mfma_f32_16x16x32_bf16 v[50:53], v[210:213], v[218:221], v[50:53]
	v_mfma_f32_16x16x32_bf16 v[38:41], v[180:183], v[226:229], v[38:41]
	v_mfma_f32_16x16x32_bf16 v[34:37], v[210:213], v[226:229], v[34:37]
	v_mfma_f32_16x16x32_bf16 v[22:25], v[180:183], v[234:237], v[22:25]
	v_mfma_f32_16x16x32_bf16 v[18:21], v[210:213], v[234:237], v[18:21]
	v_mfma_f32_16x16x32_bf16 v[6:9], v[180:183], v[242:245], v[6:9]
	v_mfma_f32_16x16x32_bf16 v[2:5], v[210:213], v[242:245], v[2:5]
	s_barrier
; #define PG8_STAGE(bufoff, gbase, voff) do { _Pragma("unroll") for (int _i = 0; _i < 2; ++_i) \
;         __builtin_amdgcn_global_load_lds((const unsigned*)((const char*)(gbase) + (voff)[_i]), (PG8_LAS unsigned*)(lds + (bufoff) + ldsw + _i * 8192), 16, 0, 0); } while (0)
; #define PG8_LDA(dst, b, h) do { _Pragma("unroll") for (int m = 0; m < 4; ++m) _Pragma("unroll") for (int k = 0; k < 2; ++k) dst[m][k] = *(const PG8_LAS bf16x8*)(lds + PG8_SA(b, h) + aoff + m * 2048 + k * 1024); } while (0)
; #define PG8_LDB(dst, b, h) do { _Pragma("unroll") for (int n = 0; n < 2; ++n) _Pragma("unroll") for (int k = 0; k < 2; ++k) dst[n][k] = *(const PG8_LAS bf16x8*)(lds + PG8_SB(b, h) + boff + n * 2048 + k * 1024); } while (0)
; #define PG8_MMA(ai, bj, At, Bt) do { __builtin_amdgcn_s_setprio(1); _Pragma("unroll") for (int m = 0; m < 4; ++m) _Pragma("unroll") for (int n = 0; n < 2; ++n) _Pragma("unroll") for (int k = 0; k < 2; ++k) \
;         acc[ai][bj][m][n] = __builtin_amdgcn_mfma_f32_16x16x32_bf16(Bt[n][k], At[m][k], acc[ai][bj][m][n], 0, 0, 0); __builtin_amdgcn_s_setprio(0); } while (0)
; #define PG8_WAIT_V(n) asm volatile("s_waitcnt vmcnt(" #n ")" ::: "memory")
; #define PG8_WAIT_L(n) asm volatile("s_waitcnt lgkmcnt(" #n ")" ::: "memory")
; #define PG8_BAR __builtin_amdgcn_s_barrier()
; #define PG8_SCHED __builtin_amdgcn_sched_barrier(0)
; template <class Epi, class Sched, bool ALIGN_EPI = false, bool SP2 = false>
; __device__ __forceinline__ void gemm_phase(PG8_LAS unsigned char* lds, const Gemm g, const Sched& S, const Epi& E) {
;     ...
;             PG8_LDB(B0, 1, 0); PG8_LDB(B1, 1, 1); PG8_SCHED; PG8_LDA(At, 1, 0); PG8_STAGE(PG8_SA(0, 1), a2 + hstep, voffA);
;             PG8_WAIT_V(8); PG8_WAIT_L(0); PG8_BAR; PG8_MMA(0, 0, At, B0); PG8_MMA(0, 1, At, B1); PG8_BAR; PG8_SCHED;
	v_or_b32_e32 v140, 0x18000, v145
	v_add_u32_e32 v147, 0x18400, v145
	ds_read_b128 v[160:163], v140
	ds_read_b128 v[164:167], v147
	v_add_u32_e32 v140, 0x18800, v145
	v_add_u32_e32 v147, 0x18c00, v145
	ds_read_b128 v[168:171], v140
	ds_read_b128 v[172:175], v147
	v_or_b32_e32 v140, 0x1c000, v145
	v_add_u32_e32 v147, 0x1c400, v145
	ds_read_b128 v[176:179], v140
	ds_read_b128 v[180:183], v147
	v_add_u32_e32 v140, 0x1c800, v145
	v_add_u32_e32 v147, 0x1cc00, v145
	ds_read_b128 v[206:209], v140
	ds_read_b128 v[210:213], v147
	s_add_u32 s12, s12, s54
	s_addc_u32 s13, s13, 0
	s_mov_b32 m0, s46
	v_lshl_add_u64 v[194:195], s[12:13], 0, v[130:131]
	ds_read_b128 v[214:217], v144 offset:32768
	ds_read_b128 v[218:221], v144 offset:33792
	ds_read_b128 v[222:225], v144 offset:34816
	ds_read_b128 v[226:229], v144 offset:35840
	ds_read_b128 v[230:233], v144 offset:36864
	ds_read_b128 v[234:237], v144 offset:37888
	ds_read_b128 v[238:241], v144 offset:38912
	ds_read_b128 v[242:245], v144 offset:39936
	global_load_lds_dwordx4 v[194:195], off
	v_lshl_add_u64 v[194:195], s[12:13], 0, v[132:133]
	s_mov_b32 m0, s47
	s_nop 0
	global_load_lds_dwordx4 v[194:195], off
	s_waitcnt vmcnt(8)
	s_waitcnt lgkmcnt(0)
	s_barrier
	s_waitcnt lgkmcnt(0)
	v_mfma_f32_16x16x32_bf16 v[126:129], v[160:163], v[214:217], v[126:129]
	v_mfma_f32_16x16x32_bf16 v[122:125], v[168:171], v[214:217], v[122:125]
	v_mfma_f32_16x16x32_bf16 v[110:113], v[160:163], v[222:225], v[110:113]
	v_mfma_f32_16x16x32_bf16 v[106:109], v[168:171], v[222:225], v[106:109]
	v_mfma_f32_16x16x32_bf16 v[94:97], v[160:163], v[230:233], v[94:97]
	v_mfma_f32_16x16x32_bf16 v[90:93], v[168:171], v[230:233], v[90:93]
	v_mfma_f32_16x16x32_bf16 v[78:81], v[160:163], v[238:241], v[78:81]
	v_mfma_f32_16x16x32_bf16 v[74:77], v[168:171], v[238:241], v[74:77]
	v_mfma_f32_16x16x32_bf16 v[126:129], v[164:167], v[218:221], v[126:129]
	v_mfma_f32_16x16x32_bf16 v[122:125], v[172:175], v[218:221], v[122:125]
	v_mfma_f32_16x16x32_bf16 v[110:113], v[164:167], v[226:229], v[110:113]
	v_mfma_f32_16x16x32_bf16 v[106:109], v[172:175], v[226:229], v[106:109]
	v_mfma_f32_16x16x32_bf16 v[94:97], v[164:167], v[234:237], v[94:97]
	v_mfma_f32_16x16x32_bf16 v[90:93], v[172:175], v[234:237], v[90:93]
	v_mfma_f32_16x16x32_bf16 v[78:81], v[164:167], v[242:245], v[78:81]
	v_mfma_f32_16x16x32_bf16 v[74:77], v[172:175], v[242:245], v[74:77]
	v_mfma_f32_16x16x32_bf16 v[118:121], v[176:179], v[214:217], v[118:121]
	v_mfma_f32_16x16x32_bf16 v[114:117], v[206:209], v[214:217], v[114:117]
	v_mfma_f32_16x16x32_bf16 v[102:105], v[176:179], v[222:225], v[102:105]
	v_mfma_f32_16x16x32_bf16 v[98:101], v[206:209], v[222:225], v[98:101]
	v_mfma_f32_16x16x32_bf16 v[86:89], v[176:179], v[230:233], v[86:89]
	v_mfma_f32_16x16x32_bf16 v[82:85], v[206:209], v[230:233], v[82:85]
	v_mfma_f32_16x16x32_bf16 v[70:73], v[176:179], v[238:241], v[70:73]
	v_mfma_f32_16x16x32_bf16 v[66:69], v[206:209], v[238:241], v[66:69]
	v_mfma_f32_16x16x32_bf16 v[118:121], v[180:183], v[218:221], v[118:121]
	v_mfma_f32_16x16x32_bf16 v[114:117], v[210:213], v[218:221], v[114:117]
	v_mfma_f32_16x16x32_bf16 v[102:105], v[180:183], v[226:229], v[102:105]
	v_mfma_f32_16x16x32_bf16 v[98:101], v[210:213], v[226:229], v[98:101]
	v_mfma_f32_16x16x32_bf16 v[86:89], v[180:183], v[234:237], v[86:89]
	v_mfma_f32_16x16x32_bf16 v[82:85], v[210:213], v[234:237], v[82:85]
	v_mfma_f32_16x16x32_bf16 v[70:73], v[180:183], v[242:245], v[70:73]
	v_mfma_f32_16x16x32_bf16 v[66:69], v[210:213], v[242:245], v[66:69]
	s_barrier
; #define PG8_STAGE(bufoff, gbase, voff) do { _Pragma("unroll") for (int _i = 0; _i < 2; ++_i) \
;         __builtin_amdgcn_global_load_lds((const unsigned*)((const char*)(gbase) + (voff)[_i]), (PG8_LAS unsigned*)(lds + (bufoff) + ldsw + _i * 8192), 16, 0, 0); } while (0)
; #define PG8_LDA(dst, b, h) do { _Pragma("unroll") for (int m = 0; m < 4; ++m) _Pragma("unroll") for (int k = 0; k < 2; ++k) dst[m][k] = *(const PG8_LAS bf16x8*)(lds + PG8_SA(b, h) + aoff + m * 2048 + k * 1024); } while (0)
; #define PG8_MMA(ai, bj, At, Bt) do { __builtin_amdgcn_s_setprio(1); _Pragma("unroll") for (int m = 0; m < 4; ++m) _Pragma("unroll") for (int n = 0; n < 2; ++n) _Pragma("unroll") for (int k = 0; k < 2; ++k) \
;         acc[ai][bj][m][n] = __builtin_amdgcn_mfma_f32_16x16x32_bf16(Bt[n][k], At[m][k], acc[ai][bj][m][n], 0, 0, 0); __builtin_amdgcn_s_setprio(0); } while (0)
; #define PG8_WAIT_V(n) asm volatile("s_waitcnt vmcnt(" #n ")" ::: "memory")
; #define PG8_WAIT_L(n) asm volatile("s_waitcnt lgkmcnt(" #n ")" ::: "memory")
; #define PG8_BAR __builtin_amdgcn_s_barrier()
; #define PG8_SCHED __builtin_amdgcn_sched_barrier(0)
; template <class Epi, class Sched, bool ALIGN_EPI = false, bool SP2 = false>
; __device__ __forceinline__ void gemm_phase(PG8_LAS unsigned char* lds, const Gemm g, const Sched& S, const Epi& E) {
;     ...
;         for (int t = 0; t < nt; t += 2) {
;     ...
;             PG8_LDA(At, 1, 1); PG8_STAGE(PG8_SB(1, 0), b3, voffB); PG8_STAGE(PG8_SB(1, 1), b3 + hstep, voffB); PG8_STAGE(PG8_SA(1, 0), a3, voffA);
;             PG8_WAIT_V(8); PG8_WAIT_L(0); PG8_BAR; PG8_MMA(1, 0, At, B0); PG8_MMA(1, 1, At, B1); PG8_BAR; PG8_SCHED;
	s_mov_b32 m0, s49
	v_lshl_add_u64 v[142:143], v[142:143], 0, s[60:61]
	ds_read_b128 v[214:217], v144 offset:49152
	ds_read_b128 v[218:221], v144 offset:50176
	ds_read_b128 v[222:225], v144 offset:51200
	ds_read_b128 v[226:229], v144 offset:52224
	ds_read_b128 v[230:233], v144 offset:53248
	ds_read_b128 v[234:237], v144 offset:54272
	ds_read_b128 v[238:241], v144 offset:55296
	ds_read_b128 v[242:245], v144 offset:56320
	global_load_lds_dwordx4 v[142:143], off
	v_lshl_add_u64 v[142:143], v[148:149], 0, s[60:61]
	s_mov_b32 m0, s52
	s_nop 0
	global_load_lds_dwordx4 v[142:143], off
	v_lshl_add_u64 v[142:143], v[156:157], 0, s[60:61]
	s_mov_b32 m0, s63
	s_nop 0
	global_load_lds_dwordx4 v[142:143], off
	v_lshl_add_u64 v[142:143], v[246:247], 0, s[60:61]
	s_mov_b32 m0, s64
	s_nop 0
	global_load_lds_dwordx4 v[142:143], off
	v_lshl_add_u64 v[142:143], v[248:249], 0, s[60:61]
	s_mov_b32 m0, s53
	s_nop 0
	global_load_lds_dwordx4 v[142:143], off
	v_lshl_add_u64 v[142:143], v[192:193], 0, s[60:61]
	s_mov_b32 m0, s62
	s_nop 0
	global_load_lds_dwordx4 v[142:143], off
	s_waitcnt vmcnt(8)
	s_waitcnt lgkmcnt(0)
	s_barrier
	s_waitcnt lgkmcnt(0)
	v_mfma_f32_16x16x32_bf16 v[62:65], v[160:163], v[214:217], v[62:65]
	v_mfma_f32_16x16x32_bf16 v[58:61], v[168:171], v[214:217], v[58:61]
	v_mfma_f32_16x16x32_bf16 v[46:49], v[160:163], v[222:225], v[46:49]
	v_mfma_f32_16x16x32_bf16 v[42:45], v[168:171], v[222:225], v[42:45]
	v_mfma_f32_16x16x32_bf16 v[30:33], v[160:163], v[230:233], v[30:33]
	v_mfma_f32_16x16x32_bf16 v[26:29], v[168:171], v[230:233], v[26:29]
	v_mfma_f32_16x16x32_bf16 v[14:17], v[160:163], v[238:241], v[14:17]
	v_mfma_f32_16x16x32_bf16 v[10:13], v[168:171], v[238:241], v[10:13]
	v_mfma_f32_16x16x32_bf16 v[62:65], v[164:167], v[218:221], v[62:65]
	v_mfma_f32_16x16x32_bf16 v[58:61], v[172:175], v[218:221], v[58:61]
	v_mfma_f32_16x16x32_bf16 v[46:49], v[164:167], v[226:229], v[46:49]
	v_mfma_f32_16x16x32_bf16 v[42:45], v[172:175], v[226:229], v[42:45]
	v_mfma_f32_16x16x32_bf16 v[30:33], v[164:167], v[234:237], v[30:33]
	v_mfma_f32_16x16x32_bf16 v[26:29], v[172:175], v[234:237], v[26:29]
	v_mfma_f32_16x16x32_bf16 v[14:17], v[164:167], v[242:245], v[14:17]
	v_mfma_f32_16x16x32_bf16 v[10:13], v[172:175], v[242:245], v[10:13]
	v_mfma_f32_16x16x32_bf16 v[54:57], v[176:179], v[214:217], v[54:57]
	v_mfma_f32_16x16x32_bf16 v[50:53], v[206:209], v[214:217], v[50:53]
	v_mfma_f32_16x16x32_bf16 v[38:41], v[176:179], v[222:225], v[38:41]
	v_mfma_f32_16x16x32_bf16 v[34:37], v[206:209], v[222:225], v[34:37]
	v_mfma_f32_16x16x32_bf16 v[22:25], v[176:179], v[230:233], v[22:25]
	v_mfma_f32_16x16x32_bf16 v[18:21], v[206:209], v[230:233], v[18:21]
	v_mfma_f32_16x16x32_bf16 v[6:9], v[176:179], v[238:241], v[6:9]
	v_mfma_f32_16x16x32_bf16 v[2:5], v[206:209], v[238:241], v[2:5]
	v_mfma_f32_16x16x32_bf16 v[54:57], v[180:183], v[218:221], v[54:57]
	v_mfma_f32_16x16x32_bf16 v[50:53], v[210:213], v[218:221], v[50:53]
	v_mfma_f32_16x16x32_bf16 v[38:41], v[180:183], v[226:229], v[38:41]
	v_mfma_f32_16x16x32_bf16 v[34:37], v[210:213], v[226:229], v[34:37]
	v_mfma_f32_16x16x32_bf16 v[22:25], v[180:183], v[234:237], v[22:25]
	v_mfma_f32_16x16x32_bf16 v[18:21], v[210:213], v[234:237], v[18:21]
	v_mfma_f32_16x16x32_bf16 v[6:9], v[180:183], v[242:245], v[6:9]
	v_mfma_f32_16x16x32_bf16 v[2:5], v[210:213], v[242:245], v[2:5]
	s_barrier
	s_add_u32 s44, s44, 0x100
	s_addc_u32 s45, s45, 0
	s_add_u32 s69, s69, 0x100
	s_addc_u32 s72, s72, 0
	s_cmp_ge_i32 s73, s48
	s_mov_b32 s12, s73
	s_cbranch_scc0 .LBB0_456
	s_setprio 0
	v_readlane_b32 s74, v253, 60
	v_readlane_b32 s75, v253, 61
	s_branch .LBB0_461
